# v6 + split (in-proj) GEMM epilogue rewritten (rstd loads hoisted, batched shuffles) + first K iteration peeled in all four GEMM loops (accumulators start from inline 0, zero-init pass removed)
# speedup vs baseline: 1.0132x; 1.0030x over previous
; #define PG8_STAGE(bufoff, gbase, voff) do { _Pragma("unroll") for (int _i = 0; _i < 2; ++_i) \
;         __builtin_amdgcn_global_load_lds((const unsigned*)((const char*)(gbase) + (voff)[_i]), (PG8_LAS unsigned*)(lds + (bufoff) + ldsw + _i * 8192), 16, 0, 0); } while (0)
; #define PG8_WAIT_V(n) asm volatile("s_waitcnt vmcnt(" #n ")" ::: "memory")
; #define PG8_BAR __builtin_amdgcn_s_barrier()
; template <class Epi, class Sched, bool ALIGN_EPI = false, bool SP2 = false>
; __device__ __forceinline__ void gemm_phase(PG8_LAS unsigned char* lds, const Gemm g, const Sched& S, const Epi& E) {
;     ...
;     Unit cur, nxt; int ui = 0;
;     if (!S.next(0, cur)) return;
;     f32x4 acc[2][2][4][2];
; #pragma unroll
;     for (int a = 0; a < 2; ++a)
; #pragma unroll
;         for (int b = 0; b < 2; ++b)
; #pragma unroll
;             for (int m = 0; m < 4; ++m)
; #pragma unroll
;                 for (int n = 0; n < 2; ++n) acc[a][b][m][n] = (f32x4){0.f, 0.f, 0.f, 0.f};
;     ...
;         const bool has_next = S.next(ui + 1, nxt);
;         const char* nA = has_next ? (const char*)g.A + (size_t)nxt.pm * tstep : cA; const char* nB = has_next ? (const char*)g.Bt + (size_t)nxt.pn * tstep : cB;
;         for (int t = 0; t < nt; t += 2) {
;             const bool last = (t == nt - 2);
;             const char* a1 = cA + (size_t)(t + 1) * kstep;
;             const char* a2 = last ? nA : cA + (size_t)(t + 2) * kstep; const char* b2 = last ? nB : cB + (size_t)(t + 2) * kstep;
;             const char* a3 = a2 + kstep; const char* b3 = b2 + kstep;
;             if (last && has_next) S.a_ready(nxt);
;             if constexpr (SP2) {
;             PG8_LDB(B0, 0, 0); PG8_LDB(B1, 0, 1); PG8_SCHED; PG8_LDA(At, 0, 0); PG8_STAGE(PG8_SA(1, 1), a1 + hstep, voffA);
;             PG8_WAIT_V(8); PG8_WAIT_L(0); PG8_BAR; PG8_MMA(0, 0, At, B0); PG8_MMA(0, 1, At, B1); PG8_BAR; PG8_SCHED;
;             PG8_LDA(At, 0, 1); PG8_STAGE(PG8_SB(0, 0), b2, voffB); PG8_STAGE(PG8_SB(0, 1), b2 + hstep, voffB); PG8_STAGE(PG8_SA(0, 0), a2, voffA);
;             PG8_WAIT_V(8); PG8_WAIT_L(0); PG8_BAR; PG8_MMA(1, 0, At, B0); PG8_MMA(1, 1, At, B1); PG8_BAR; PG8_SCHED;
;             PG8_LDB(B0, 1, 0); PG8_LDB(B1, 1, 1); PG8_SCHED; PG8_LDA(At, 1, 0); PG8_STAGE(PG8_SA(0, 1), a2 + hstep, voffA);
;             PG8_WAIT_V(8); PG8_WAIT_L(0); PG8_BAR; PG8_MMA(0, 0, At, B0); PG8_MMA(0, 1, At, B1); PG8_BAR; PG8_SCHED;
.LBB0_41:
	s_ashr_i32 s17, s16, 31
	s_lshl_b64 s[18:19], s[16:17], s28
	s_add_u32 s18, s26, s18
	s_addc_u32 s19, s27, s19
	s_and_b64 s[20:21], s[6:7], exec
	s_cselect_b32 s17, s19, s23
	s_cselect_b32 s42, s18, s22
	s_ashr_i32 s15, s14, 31
	s_lshl_b64 s[20:21], s[14:15], s28
	v_readlane_b32 s44, v251, 2
	v_readlane_b32 s45, v251, 3
	s_add_u32 s20, s44, s20
	s_addc_u32 s21, s45, s21
	s_and_b64 s[44:45], s[6:7], exec
	s_cselect_b32 s15, s21, s25
	s_cselect_b32 s43, s20, s24
	s_add_u32 s22, s22, 0x80
	s_addc_u32 s23, s23, 0
	s_add_u32 s44, s24, 0x100
	s_addc_u32 s45, s25, 0
	s_mov_b32 s24, 0
	s_waitcnt lgkmcnt(0)
	s_add_i32 s46, s24, 2
	s_add_u32 s47, s22, 0x80
	s_addc_u32 s25, s23, 0
	s_add_i32 s50, 0, 0x10000
	s_cmp_eq_u32 s37, s24
	s_cselect_b32 s25, s17, s25
	s_cselect_b32 s24, s42, s47
	s_cselect_b32 s49, s15, s45
	s_cselect_b32 s48, s43, s44
	s_add_i32 s47, 0, 0x14000
	v_add_u32_e32 v142, s50, v165
	v_add_u32_e32 v182, s47, v165
	ds_read_b128 v[130:133], v142
	ds_read_b128 v[134:137], v142 offset:1024
	ds_read_b128 v[138:141], v142 offset:2048
	ds_read_b128 v[142:145], v142 offset:3072
	ds_read_b128 v[146:149], v182
	ds_read_b128 v[150:153], v182 offset:1024
	ds_read_b128 v[154:157], v182 offset:2048
	ds_read_b128 v[182:185], v182 offset:3072
	v_lshl_add_u64 v[198:199], s[22:23], 0, v[178:179]
	s_add_i32 m0, s29, 0xc000
	ds_read_b128 v[186:189], v214
	ds_read_b128 v[190:193], v214 offset:1024
	ds_read_b128 v[194:197], v214 offset:2048
	ds_read_b128 v[216:219], v214 offset:3072
	ds_read_b128 v[220:223], v214 offset:4096
	ds_read_b128 v[224:227], v214 offset:5120
	ds_read_b128 v[228:231], v214 offset:6144
	ds_read_b128 v[232:235], v214 offset:7168
	global_load_lds_dwordx4 v[198:199], off
	v_lshl_add_u64 v[198:199], s[22:23], 0, v[180:181]
	s_add_i32 m0, s29, 0xe000
	s_nop 0
	global_load_lds_dwordx4 v[198:199], off
	s_waitcnt vmcnt(8)
	s_waitcnt lgkmcnt(0)
	s_barrier
	s_setprio 1
	s_waitcnt lgkmcnt(0)
	v_mfma_f32_16x16x32_bf16 v[126:129], v[130:133], v[186:189], 0
	v_mfma_f32_16x16x32_bf16 v[122:125], v[138:141], v[186:189], 0
	v_mfma_f32_16x16x32_bf16 v[110:113], v[130:133], v[194:197], 0
	v_mfma_f32_16x16x32_bf16 v[106:109], v[138:141], v[194:197], 0
	v_mfma_f32_16x16x32_bf16 v[94:97], v[130:133], v[220:223], 0
	v_mfma_f32_16x16x32_bf16 v[90:93], v[138:141], v[220:223], 0
	v_mfma_f32_16x16x32_bf16 v[78:81], v[130:133], v[228:231], 0
	v_mfma_f32_16x16x32_bf16 v[74:77], v[138:141], v[228:231], 0
	v_mfma_f32_16x16x32_bf16 v[126:129], v[134:137], v[190:193], v[126:129]
	v_mfma_f32_16x16x32_bf16 v[122:125], v[142:145], v[190:193], v[122:125]
	v_mfma_f32_16x16x32_bf16 v[110:113], v[134:137], v[216:219], v[110:113]
	v_mfma_f32_16x16x32_bf16 v[106:109], v[142:145], v[216:219], v[106:109]
	v_mfma_f32_16x16x32_bf16 v[94:97], v[134:137], v[224:227], v[94:97]
	v_mfma_f32_16x16x32_bf16 v[90:93], v[142:145], v[224:227], v[90:93]
	v_mfma_f32_16x16x32_bf16 v[78:81], v[134:137], v[232:235], v[78:81]
	v_mfma_f32_16x16x32_bf16 v[74:77], v[142:145], v[232:235], v[74:77]
	s_setprio 0
	s_setprio 1
	v_mfma_f32_16x16x32_bf16 v[118:121], v[146:149], v[186:189], 0
	v_mfma_f32_16x16x32_bf16 v[114:117], v[154:157], v[186:189], 0
	v_mfma_f32_16x16x32_bf16 v[102:105], v[146:149], v[194:197], 0
	v_mfma_f32_16x16x32_bf16 v[98:101], v[154:157], v[194:197], 0
	v_mfma_f32_16x16x32_bf16 v[86:89], v[146:149], v[220:223], 0
	v_mfma_f32_16x16x32_bf16 v[82:85], v[154:157], v[220:223], 0
	v_mfma_f32_16x16x32_bf16 v[70:73], v[146:149], v[228:231], 0
	v_mfma_f32_16x16x32_bf16 v[66:69], v[154:157], v[228:231], 0
	v_mfma_f32_16x16x32_bf16 v[118:121], v[150:153], v[190:193], v[118:121]
	v_mfma_f32_16x16x32_bf16 v[114:117], v[182:185], v[190:193], v[114:117]
	v_mfma_f32_16x16x32_bf16 v[102:105], v[150:153], v[216:219], v[102:105]
	v_mfma_f32_16x16x32_bf16 v[98:101], v[182:185], v[216:219], v[98:101]
	v_mfma_f32_16x16x32_bf16 v[86:89], v[150:153], v[224:227], v[86:89]
	v_mfma_f32_16x16x32_bf16 v[82:85], v[182:185], v[224:227], v[82:85]
	v_mfma_f32_16x16x32_bf16 v[70:73], v[150:153], v[232:235], v[70:73]
	v_mfma_f32_16x16x32_bf16 v[66:69], v[182:185], v[232:235], v[66:69]
	s_setprio 0
	s_barrier
	s_add_i32 s50, s50, s2
	v_lshl_add_u64 v[198:199], s[48:49], 0, v[0:1]
	s_mov_b32 m0, s50
	ds_read_b128 v[186:189], v214 offset:16384
	ds_read_b128 v[190:193], v214 offset:17408
	ds_read_b128 v[194:197], v214 offset:18432
	ds_read_b128 v[216:219], v214 offset:19456
	ds_read_b128 v[220:223], v214 offset:20480
	ds_read_b128 v[224:227], v214 offset:21504
	ds_read_b128 v[228:231], v214 offset:22528
	ds_read_b128 v[232:235], v214 offset:23552
	global_load_lds_dwordx4 v[198:199], off
	s_add_i32 m0, s50, 0x2000
	v_lshl_add_u64 v[236:237], s[48:49], 0, v[172:173]
	s_add_u32 s48, s48, s8
	s_addc_u32 s49, s49, 0
	s_add_i32 s47, s47, s2
	global_load_lds_dwordx4 v[236:237], off
	v_lshl_add_u64 v[238:239], s[48:49], 0, v[0:1]
	s_mov_b32 m0, s47
	v_lshl_add_u64 v[240:241], s[48:49], 0, v[172:173]
	global_load_lds_dwordx4 v[238:239], off
	s_add_i32 m0, s47, 0x2000
	v_lshl_add_u64 v[242:243], s[24:25], 0, v[176:177]
	global_load_lds_dwordx4 v[240:241], off
	s_mov_b32 m0, s29
	v_lshl_add_u64 v[244:245], s[24:25], 0, v[174:175]
	global_load_lds_dwordx4 v[242:243], off
	s_mov_b32 m0, s30
	s_nop 0
	global_load_lds_dwordx4 v[244:245], off
	s_waitcnt vmcnt(8)
	s_waitcnt lgkmcnt(0)
	s_barrier
; #define PG8_STAGE(bufoff, gbase, voff) do { _Pragma("unroll") for (int _i = 0; _i < 2; ++_i) \
;         __builtin_amdgcn_global_load_lds((const unsigned*)((const char*)(gbase) + (voff)[_i]), (PG8_LAS unsigned*)(lds + (bufoff) + ldsw + _i * 8192), 16, 0, 0); } while (0)
; #define PG8_LDA(dst, b, h) do { _Pragma("unroll") for (int m = 0; m < 4; ++m) _Pragma("unroll") for (int k = 0; k < 2; ++k) dst[m][k] = *(const PG8_LAS bf16x8*)(lds + PG8_SA(b, h) + aoff + m * 2048 + k * 1024); } while (0)
; #define PG8_LDB(dst, b, h) do { _Pragma("unroll") for (int n = 0; n < 2; ++n) _Pragma("unroll") for (int k = 0; k < 2; ++k) dst[n][k] = *(const PG8_LAS bf16x8*)(lds + PG8_SB(b, h) + boff + n * 2048 + k * 1024); } while (0)
; #define PG8_MMA(ai, bj, At, Bt) do { __builtin_amdgcn_s_setprio(1); _Pragma("unroll") for (int m = 0; m < 4; ++m) _Pragma("unroll") for (int n = 0; n < 2; ++n) _Pragma("unroll") for (int k = 0; k < 2; ++k) \
;         acc[ai][bj][m][n] = __builtin_amdgcn_mfma_f32_16x16x32_bf16(Bt[n][k], At[m][k], acc[ai][bj][m][n], 0, 0, 0); __builtin_amdgcn_s_setprio(0); } while (0)
; #define PG8_WAIT_V(n) asm volatile("s_waitcnt vmcnt(" #n ")" ::: "memory")
; #define PG8_WAIT_L(n) asm volatile("s_waitcnt lgkmcnt(" #n ")" ::: "memory")
; #define PG8_BAR __builtin_amdgcn_s_barrier()
; #define PG8_SCHED __builtin_amdgcn_sched_barrier(0)
; template <class Epi, class Sched, bool ALIGN_EPI = false, bool SP2 = false>
; __device__ __forceinline__ void gemm_phase(PG8_LAS unsigned char* lds, const Gemm g, const Sched& S, const Epi& E) {
;     ...
;             PG8_WAIT_V(8); PG8_WAIT_L(0); PG8_BAR; PG8_MMA(1, 0, At, B0); PG8_MMA(1, 1, At, B1); PG8_BAR; PG8_SCHED;
;             PG8_LDB(B0, 1, 0); PG8_LDB(B1, 1, 1); PG8_SCHED; PG8_LDA(At, 1, 0); PG8_STAGE(PG8_SA(0, 1), a2 + hstep, voffA);
;             PG8_WAIT_V(8); PG8_WAIT_L(0); PG8_BAR; PG8_MMA(0, 0, At, B0); PG8_MMA(0, 1, At, B1); PG8_BAR; PG8_SCHED;
;             PG8_LDA(At, 1, 1); PG8_STAGE(PG8_SB(1, 0), b3, voffB); PG8_STAGE(PG8_SB(1, 1), b3 + hstep, voffB); PG8_STAGE(PG8_SA(1, 0), a3, voffA);
;             PG8_WAIT_V(8); PG8_WAIT_L(0); PG8_BAR; PG8_MMA(1, 0, At, B0); PG8_MMA(1, 1, At, B1); PG8_BAR; PG8_SCHED;
	s_setprio 1
	s_waitcnt lgkmcnt(0)
	v_mfma_f32_16x16x32_bf16 v[62:65], v[130:133], v[186:189], 0
	v_mfma_f32_16x16x32_bf16 v[58:61], v[138:141], v[186:189], 0
	v_mfma_f32_16x16x32_bf16 v[46:49], v[130:133], v[194:197], 0
	v_mfma_f32_16x16x32_bf16 v[42:45], v[138:141], v[194:197], 0
	v_mfma_f32_16x16x32_bf16 v[30:33], v[130:133], v[220:223], 0
	v_mfma_f32_16x16x32_bf16 v[26:29], v[138:141], v[220:223], 0
	v_mfma_f32_16x16x32_bf16 v[14:17], v[130:133], v[228:231], 0
	v_mfma_f32_16x16x32_bf16 v[10:13], v[138:141], v[228:231], 0
	v_mfma_f32_16x16x32_bf16 v[62:65], v[134:137], v[190:193], v[62:65]
	v_mfma_f32_16x16x32_bf16 v[58:61], v[142:145], v[190:193], v[58:61]
	v_mfma_f32_16x16x32_bf16 v[46:49], v[134:137], v[216:219], v[46:49]
	v_mfma_f32_16x16x32_bf16 v[42:45], v[142:145], v[216:219], v[42:45]
	v_mfma_f32_16x16x32_bf16 v[30:33], v[134:137], v[224:227], v[30:33]
	v_mfma_f32_16x16x32_bf16 v[26:29], v[142:145], v[224:227], v[26:29]
	v_mfma_f32_16x16x32_bf16 v[14:17], v[134:137], v[232:235], v[14:17]
	v_mfma_f32_16x16x32_bf16 v[10:13], v[142:145], v[232:235], v[10:13]
	s_setprio 0
	s_setprio 1
	v_mfma_f32_16x16x32_bf16 v[54:57], v[146:149], v[186:189], 0
	v_mfma_f32_16x16x32_bf16 v[50:53], v[154:157], v[186:189], 0
	v_mfma_f32_16x16x32_bf16 v[38:41], v[146:149], v[194:197], 0
	v_mfma_f32_16x16x32_bf16 v[34:37], v[154:157], v[194:197], 0
	v_mfma_f32_16x16x32_bf16 v[22:25], v[146:149], v[220:223], 0
	v_mfma_f32_16x16x32_bf16 v[18:21], v[154:157], v[220:223], 0
	v_mfma_f32_16x16x32_bf16 v[6:9], v[146:149], v[228:231], 0
	v_mfma_f32_16x16x32_bf16 v[2:5], v[154:157], v[228:231], 0
	v_mfma_f32_16x16x32_bf16 v[54:57], v[150:153], v[190:193], v[54:57]
	v_mfma_f32_16x16x32_bf16 v[50:53], v[182:185], v[190:193], v[50:53]
	v_mfma_f32_16x16x32_bf16 v[38:41], v[150:153], v[216:219], v[38:41]
	v_mfma_f32_16x16x32_bf16 v[34:37], v[182:185], v[216:219], v[34:37]
	v_mfma_f32_16x16x32_bf16 v[22:25], v[150:153], v[224:227], v[22:25]
	v_mfma_f32_16x16x32_bf16 v[18:21], v[182:185], v[224:227], v[18:21]
	v_mfma_f32_16x16x32_bf16 v[6:9], v[150:153], v[232:235], v[6:9]
	v_mfma_f32_16x16x32_bf16 v[2:5], v[182:185], v[232:235], v[2:5]
	s_setprio 0
	s_barrier
	s_add_i32 s47, 0, 0x18000
	s_add_i32 s48, 0, 0x1c000
	v_add_u32_e32 v142, s47, v165
	v_add_u32_e32 v182, s48, v165
	ds_read_b128 v[130:133], v142
	ds_read_b128 v[134:137], v142 offset:1024
	ds_read_b128 v[138:141], v142 offset:2048
	ds_read_b128 v[142:145], v142 offset:3072
	ds_read_b128 v[146:149], v182
	ds_read_b128 v[150:153], v182 offset:1024
	ds_read_b128 v[154:157], v182 offset:2048
	ds_read_b128 v[182:185], v182 offset:3072
	s_add_u32 s24, s24, s8
	s_addc_u32 s25, s25, 0
	s_mov_b32 m0, s31
	v_lshl_add_u64 v[246:247], s[24:25], 0, v[176:177]
	ds_read_b128 v[186:189], v214 offset:32768
	ds_read_b128 v[190:193], v214 offset:33792
	ds_read_b128 v[194:197], v214 offset:34816
	ds_read_b128 v[216:219], v214 offset:35840
	ds_read_b128 v[220:223], v214 offset:36864
	ds_read_b128 v[224:227], v214 offset:37888
	ds_read_b128 v[228:231], v214 offset:38912
	ds_read_b128 v[232:235], v214 offset:39936
	global_load_lds_dwordx4 v[246:247], off
	v_lshl_add_u64 v[246:247], s[24:25], 0, v[174:175]
	s_mov_b32 m0, s34
	s_nop 0
	global_load_lds_dwordx4 v[246:247], off
	s_waitcnt vmcnt(8)
	s_waitcnt lgkmcnt(0)
	s_barrier
	s_setprio 1
	s_waitcnt lgkmcnt(0)
	v_mfma_f32_16x16x32_bf16 v[126:129], v[130:133], v[186:189], v[126:129]
	v_mfma_f32_16x16x32_bf16 v[122:125], v[138:141], v[186:189], v[122:125]
	v_mfma_f32_16x16x32_bf16 v[110:113], v[130:133], v[194:197], v[110:113]
	v_mfma_f32_16x16x32_bf16 v[106:109], v[138:141], v[194:197], v[106:109]
	v_mfma_f32_16x16x32_bf16 v[94:97], v[130:133], v[220:223], v[94:97]
	v_mfma_f32_16x16x32_bf16 v[90:93], v[138:141], v[220:223], v[90:93]
	v_mfma_f32_16x16x32_bf16 v[78:81], v[130:133], v[228:231], v[78:81]
	v_mfma_f32_16x16x32_bf16 v[74:77], v[138:141], v[228:231], v[74:77]
	v_mfma_f32_16x16x32_bf16 v[126:129], v[134:137], v[190:193], v[126:129]
	v_mfma_f32_16x16x32_bf16 v[122:125], v[142:145], v[190:193], v[122:125]
	v_mfma_f32_16x16x32_bf16 v[110:113], v[134:137], v[216:219], v[110:113]
	v_mfma_f32_16x16x32_bf16 v[106:109], v[142:145], v[216:219], v[106:109]
	v_mfma_f32_16x16x32_bf16 v[94:97], v[134:137], v[224:227], v[94:97]
	v_mfma_f32_16x16x32_bf16 v[90:93], v[142:145], v[224:227], v[90:93]
	v_mfma_f32_16x16x32_bf16 v[78:81], v[134:137], v[232:235], v[78:81]
	v_mfma_f32_16x16x32_bf16 v[74:77], v[142:145], v[232:235], v[74:77]
	s_setprio 0
	s_setprio 1
	v_mfma_f32_16x16x32_bf16 v[118:121], v[146:149], v[186:189], v[118:121]
	v_mfma_f32_16x16x32_bf16 v[114:117], v[154:157], v[186:189], v[114:117]
	v_mfma_f32_16x16x32_bf16 v[102:105], v[146:149], v[194:197], v[102:105]
	v_mfma_f32_16x16x32_bf16 v[98:101], v[154:157], v[194:197], v[98:101]
	v_mfma_f32_16x16x32_bf16 v[86:89], v[146:149], v[220:223], v[86:89]
	v_mfma_f32_16x16x32_bf16 v[82:85], v[154:157], v[220:223], v[82:85]
	v_mfma_f32_16x16x32_bf16 v[70:73], v[146:149], v[228:231], v[70:73]
	v_mfma_f32_16x16x32_bf16 v[66:69], v[154:157], v[228:231], v[66:69]
	v_mfma_f32_16x16x32_bf16 v[118:121], v[150:153], v[190:193], v[118:121]
	v_mfma_f32_16x16x32_bf16 v[114:117], v[182:185], v[190:193], v[114:117]
	v_mfma_f32_16x16x32_bf16 v[102:105], v[150:153], v[216:219], v[102:105]
	v_mfma_f32_16x16x32_bf16 v[98:101], v[182:185], v[216:219], v[98:101]
	v_mfma_f32_16x16x32_bf16 v[86:89], v[150:153], v[224:227], v[86:89]
	v_mfma_f32_16x16x32_bf16 v[82:85], v[182:185], v[224:227], v[82:85]
	v_mfma_f32_16x16x32_bf16 v[70:73], v[150:153], v[232:235], v[70:73]
	v_mfma_f32_16x16x32_bf16 v[66:69], v[182:185], v[232:235], v[66:69]
	s_setprio 0
	s_barrier
; #define PG8_STAGE(bufoff, gbase, voff) do { _Pragma("unroll") for (int _i = 0; _i < 2; ++_i) \
;         __builtin_amdgcn_global_load_lds((const unsigned*)((const char*)(gbase) + (voff)[_i]), (PG8_LAS unsigned*)(lds + (bufoff) + ldsw + _i * 8192), 16, 0, 0); } while (0)
; #define PG8_LDA(dst, b, h) do { _Pragma("unroll") for (int m = 0; m < 4; ++m) _Pragma("unroll") for (int k = 0; k < 2; ++k) dst[m][k] = *(const PG8_LAS bf16x8*)(lds + PG8_SA(b, h) + aoff + m * 2048 + k * 1024); } while (0)
; #define PG8_MMA(ai, bj, At, Bt) do { __builtin_amdgcn_s_setprio(1); _Pragma("unroll") for (int m = 0; m < 4; ++m) _Pragma("unroll") for (int n = 0; n < 2; ++n) _Pragma("unroll") for (int k = 0; k < 2; ++k) \
;         acc[ai][bj][m][n] = __builtin_amdgcn_mfma_f32_16x16x32_bf16(Bt[n][k], At[m][k], acc[ai][bj][m][n], 0, 0, 0); __builtin_amdgcn_s_setprio(0); } while (0)
; #define PG8_WAIT_V(n) asm volatile("s_waitcnt vmcnt(" #n ")" ::: "memory")
; #define PG8_WAIT_L(n) asm volatile("s_waitcnt lgkmcnt(" #n ")" ::: "memory")
; #define PG8_BAR __builtin_amdgcn_s_barrier()
; #define PG8_SCHED __builtin_amdgcn_sched_barrier(0)
; template <class Epi, class Sched, bool ALIGN_EPI = false, bool SP2 = false>
; __device__ __forceinline__ void gemm_phase(PG8_LAS unsigned char* lds, const Gemm g, const Sched& S, const Epi& E) {
;     ...
;         for (int t = 0; t < nt; t += 2) {
;     ...
;             PG8_LDA(At, 1, 1); PG8_STAGE(PG8_SB(1, 0), b3, voffB); PG8_STAGE(PG8_SB(1, 1), b3 + hstep, voffB); PG8_STAGE(PG8_SA(1, 0), a3, voffA);
;             PG8_WAIT_V(8); PG8_WAIT_L(0); PG8_BAR; PG8_MMA(1, 0, At, B0); PG8_MMA(1, 1, At, B1); PG8_BAR; PG8_SCHED;
	s_add_i32 s24, s47, s2
	v_lshl_add_u64 v[198:199], v[198:199], 0, s[90:91]
	s_mov_b32 m0, s24
	ds_read_b128 v[186:189], v214 offset:49152
	ds_read_b128 v[190:193], v214 offset:50176
	ds_read_b128 v[194:197], v214 offset:51200
	ds_read_b128 v[216:219], v214 offset:52224
	ds_read_b128 v[220:223], v214 offset:53248
	ds_read_b128 v[224:227], v214 offset:54272
	ds_read_b128 v[228:231], v214 offset:55296
	ds_read_b128 v[232:235], v214 offset:56320
	global_load_lds_dwordx4 v[198:199], off
	v_lshl_add_u64 v[198:199], v[236:237], 0, s[90:91]
	s_add_i32 m0, s24, 0x2000
	s_add_i32 s24, s48, s2
	global_load_lds_dwordx4 v[198:199], off
	v_lshl_add_u64 v[198:199], v[238:239], 0, s[90:91]
	s_mov_b32 m0, s24
	s_nop 0
	global_load_lds_dwordx4 v[198:199], off
	v_lshl_add_u64 v[198:199], v[240:241], 0, s[90:91]
	s_add_i32 m0, s24, 0x2000
	s_nop 0
	global_load_lds_dwordx4 v[198:199], off
	v_lshl_add_u64 v[198:199], v[242:243], 0, s[90:91]
	s_mov_b32 m0, s38
	s_nop 0
	global_load_lds_dwordx4 v[198:199], off
	v_lshl_add_u64 v[198:199], v[244:245], 0, s[90:91]
	s_mov_b32 m0, s39
	s_nop 0
	global_load_lds_dwordx4 v[198:199], off
	s_waitcnt vmcnt(8)
	s_waitcnt lgkmcnt(0)
	s_barrier
	s_setprio 1
	s_waitcnt lgkmcnt(0)
	v_mfma_f32_16x16x32_bf16 v[62:65], v[130:133], v[186:189], v[62:65]
	v_mfma_f32_16x16x32_bf16 v[58:61], v[138:141], v[186:189], v[58:61]
	v_mfma_f32_16x16x32_bf16 v[46:49], v[130:133], v[194:197], v[46:49]
	v_mfma_f32_16x16x32_bf16 v[42:45], v[138:141], v[194:197], v[42:45]
	v_mfma_f32_16x16x32_bf16 v[30:33], v[130:133], v[220:223], v[30:33]
	v_mfma_f32_16x16x32_bf16 v[26:29], v[138:141], v[220:223], v[26:29]
	v_mfma_f32_16x16x32_bf16 v[14:17], v[130:133], v[228:231], v[14:17]
	v_mfma_f32_16x16x32_bf16 v[10:13], v[138:141], v[228:231], v[10:13]
	v_mfma_f32_16x16x32_bf16 v[62:65], v[134:137], v[190:193], v[62:65]
	v_mfma_f32_16x16x32_bf16 v[58:61], v[142:145], v[190:193], v[58:61]
	v_mfma_f32_16x16x32_bf16 v[46:49], v[134:137], v[216:219], v[46:49]
	v_mfma_f32_16x16x32_bf16 v[42:45], v[142:145], v[216:219], v[42:45]
	v_mfma_f32_16x16x32_bf16 v[30:33], v[134:137], v[224:227], v[30:33]
	v_mfma_f32_16x16x32_bf16 v[26:29], v[142:145], v[224:227], v[26:29]
	v_mfma_f32_16x16x32_bf16 v[14:17], v[134:137], v[232:235], v[14:17]
	v_mfma_f32_16x16x32_bf16 v[10:13], v[142:145], v[232:235], v[10:13]
	s_setprio 0
	s_setprio 1
	v_mfma_f32_16x16x32_bf16 v[54:57], v[146:149], v[186:189], v[54:57]
	v_mfma_f32_16x16x32_bf16 v[50:53], v[154:157], v[186:189], v[50:53]
	v_mfma_f32_16x16x32_bf16 v[38:41], v[146:149], v[194:197], v[38:41]
	v_mfma_f32_16x16x32_bf16 v[34:37], v[154:157], v[194:197], v[34:37]
	v_mfma_f32_16x16x32_bf16 v[22:25], v[146:149], v[220:223], v[22:25]
	v_mfma_f32_16x16x32_bf16 v[18:21], v[154:157], v[220:223], v[18:21]
	v_mfma_f32_16x16x32_bf16 v[6:9], v[146:149], v[228:231], v[6:9]
	v_mfma_f32_16x16x32_bf16 v[2:5], v[154:157], v[228:231], v[2:5]
	v_mfma_f32_16x16x32_bf16 v[54:57], v[150:153], v[190:193], v[54:57]
	v_mfma_f32_16x16x32_bf16 v[50:53], v[182:185], v[190:193], v[50:53]
	v_mfma_f32_16x16x32_bf16 v[38:41], v[150:153], v[216:219], v[38:41]
	v_mfma_f32_16x16x32_bf16 v[34:37], v[182:185], v[216:219], v[34:37]
	v_mfma_f32_16x16x32_bf16 v[22:25], v[150:153], v[224:227], v[22:25]
	v_mfma_f32_16x16x32_bf16 v[18:21], v[182:185], v[224:227], v[18:21]
	v_mfma_f32_16x16x32_bf16 v[6:9], v[150:153], v[232:235], v[6:9]
	v_mfma_f32_16x16x32_bf16 v[2:5], v[182:185], v[232:235], v[2:5]
	s_setprio 0
	s_barrier
	s_add_u32 s22, s22, 0x100
	s_addc_u32 s23, s23, 0
	s_add_u32 s44, s44, 0x100
	s_addc_u32 s45, s45, 0
	s_mov_b32 s24, s46

; #define PG8_STAGE(bufoff, gbase, voff) do { _Pragma("unroll") for (int _i = 0; _i < 2; ++_i) \
;         __builtin_amdgcn_global_load_lds((const unsigned*)((const char*)(gbase) + (voff)[_i]), (PG8_LAS unsigned*)(lds + (bufoff) + ldsw + _i * 8192), 16, 0, 0); } while (0)
; #define PG8_LDA(dst, b, h) do { _Pragma("unroll") for (int m = 0; m < 4; ++m) _Pragma("unroll") for (int k = 0; k < 2; ++k) dst[m][k] = *(const PG8_LAS bf16x8*)(lds + PG8_SA(b, h) + aoff + m * 2048 + k * 1024); } while (0)
; #define PG8_WAIT_V(n) asm volatile("s_waitcnt vmcnt(" #n ")" ::: "memory")
; #define PG8_WAIT_L(n) asm volatile("s_waitcnt lgkmcnt(" #n ")" ::: "memory")
; template <class Epi, class Sched, bool ALIGN_EPI = false, bool SP2 = false>
; __device__ __forceinline__ void gemm_phase(PG8_LAS unsigned char* lds, const Gemm g, const Sched& S, const Epi& E) {
;     ...
;         const bool has_next = S.next(ui + 1, nxt);
;         const char* nA = has_next ? (const char*)g.A + (size_t)nxt.pm * tstep : cA; const char* nB = has_next ? (const char*)g.Bt + (size_t)nxt.pn * tstep : cB;
;         for (int t = 0; t < nt; t += 2) {
;             const bool last = (t == nt - 2);
;             const char* a1 = cA + (size_t)(t + 1) * kstep;
;             const char* a2 = last ? nA : cA + (size_t)(t + 2) * kstep; const char* b2 = last ? nB : cB + (size_t)(t + 2) * kstep;
;             const char* a3 = a2 + kstep; const char* b3 = b2 + kstep;
;             if (last && has_next) S.a_ready(nxt);
;             if constexpr (SP2) {
;             PG8_LDB(B0, 0, 0); PG8_LDB(B1, 0, 1); PG8_SCHED; PG8_LDA(At, 0, 0); PG8_STAGE(PG8_SA(1, 1), a1 + hstep, voffA);
;             PG8_WAIT_V(8); PG8_WAIT_L(0); PG8_BAR; PG8_MMA(0, 0, At, B0); PG8_MMA(0, 1, At, B1); PG8_BAR; PG8_SCHED;
;             PG8_LDA(At, 0, 1); PG8_STAGE(PG8_SB(0, 0), b2, voffB); PG8_STAGE(PG8_SB(0, 1), b2 + hstep, voffB); PG8_STAGE(PG8_SA(0, 0), a2, voffA);
;             PG8_WAIT_V(8); PG8_WAIT_L(0); PG8_BAR; PG8_MMA(1, 0, At, B0); PG8_MMA(1, 1, At, B1); PG8_BAR; PG8_SCHED;
;     ...
; #pragma unroll
;         for (int a = 0; a < 2; ++a)
; #pragma unroll
;             for (int b = 0; b < 2; ++b)
; #pragma unroll
;                 for (int m = 0; m < 4; ++m)
; #pragma unroll
;                     for (int n = 0; n < 2; ++n) acc[a][b][m][n] = (f32x4){0.f, 0.f, 0.f, 0.f};
;         cur = nxt; cA = nA; cB = nB; ++ui;
.LBB0_329:
	s_ashr_i32 s21, s20, 31
	s_lshl_b64 s[22:23], s[20:21], 19
	s_add_u32 s22, s94, s22
	s_addc_u32 s23, s95, s23
	s_and_b64 s[24:25], s[4:5], exec
	s_cselect_b32 s21, s23, s29
	s_cselect_b32 s27, s22, s28
	s_ashr_i32 s19, s18, 31
	s_lshl_b64 s[24:25], s[18:19], 19
	v_readlane_b32 s34, v251, 0
	v_readlane_b32 s35, v251, 1
	s_add_u32 s24, s34, s24
	s_addc_u32 s25, s35, s25
	s_and_b64 s[34:35], s[4:5], exec
	s_cselect_b32 s19, s25, s31
	s_cselect_b32 s60, s24, s30
	s_add_u32 s28, s28, 0x40080
	s_addc_u32 s29, s29, 0
	s_add_u32 s61, s30, 0x100
	s_waitcnt vmcnt(0)
	s_addc_u32 s62, s31, 0
	s_mov_b32 s63, -2
	s_add_u32 s30, s28, 0xfffc0080
	s_addc_u32 s31, s29, -1
	s_add_i32 s64, 0, 0x10000
	s_cmp_eq_u32 s63, 12
	s_cselect_b32 s35, s21, s31
	s_cselect_b32 s34, s27, s30
	v_add_u32_e32 v156, s64, v149
	s_cselect_b32 s31, s19, s62
	s_cselect_b32 s30, s60, s61
	s_add_i32 s66, 0, 0x14000
	ds_read_b128 v[144:147], v156
	ds_read_b128 v[152:155], v156 offset:1024
	ds_read_b128 v[172:175], v156 offset:2048
	ds_read_b128 v[176:179], v156 offset:3072
	v_add_u32_e32 v156, s66, v149
	ds_read_b128 v[180:183], v156
	ds_read_b128 v[184:187], v156 offset:1024
	ds_read_b128 v[188:191], v156 offset:2048
	ds_read_b128 v[192:195], v156 offset:3072
	v_lshl_add_u64 v[156:157], s[28:29], 0, v[140:141]
	s_add_i32 m0, s46, 0xc000
	ds_read_b128 v[196:199], v151
	ds_read_b128 v[214:217], v151 offset:1024
	ds_read_b128 v[218:221], v151 offset:2048
	ds_read_b128 v[222:225], v151 offset:3072
	ds_read_b128 v[226:229], v151 offset:4096
	ds_read_b128 v[230:233], v151 offset:5120
	ds_read_b128 v[234:237], v151 offset:6144
	ds_read_b128 v[238:241], v151 offset:7168
	global_load_lds_dwordx4 v[156:157], off
	v_lshl_add_u64 v[156:157], s[28:29], 0, v[142:143]
	s_add_i32 m0, s46, 0xe000
	s_nop 0
	global_load_lds_dwordx4 v[156:157], off
	s_waitcnt vmcnt(8)
	s_waitcnt lgkmcnt(0)
	s_barrier
	s_setprio 1
	s_waitcnt lgkmcnt(0)
	v_mfma_f32_16x16x32_bf16 v[62:65], v[144:147], v[196:199], 0
	v_mfma_f32_16x16x32_bf16 v[58:61], v[172:175], v[196:199], 0
	v_mfma_f32_16x16x32_bf16 v[54:57], v[144:147], v[218:221], 0
	v_mfma_f32_16x16x32_bf16 v[50:53], v[172:175], v[218:221], 0
	v_mfma_f32_16x16x32_bf16 v[46:49], v[144:147], v[226:229], 0
	v_mfma_f32_16x16x32_bf16 v[42:45], v[172:175], v[226:229], 0
	v_mfma_f32_16x16x32_bf16 v[38:41], v[144:147], v[234:237], 0
	v_mfma_f32_16x16x32_bf16 v[34:37], v[172:175], v[234:237], 0
	v_mfma_f32_16x16x32_bf16 v[62:65], v[152:155], v[214:217], v[62:65]
	v_mfma_f32_16x16x32_bf16 v[58:61], v[176:179], v[214:217], v[58:61]
	v_mfma_f32_16x16x32_bf16 v[54:57], v[152:155], v[222:225], v[54:57]
	v_mfma_f32_16x16x32_bf16 v[50:53], v[176:179], v[222:225], v[50:53]
	v_mfma_f32_16x16x32_bf16 v[46:49], v[152:155], v[230:233], v[46:49]
	v_mfma_f32_16x16x32_bf16 v[42:45], v[176:179], v[230:233], v[42:45]
	v_mfma_f32_16x16x32_bf16 v[38:41], v[152:155], v[238:241], v[38:41]
	v_mfma_f32_16x16x32_bf16 v[34:37], v[176:179], v[238:241], v[34:37]
	s_setprio 0
	s_setprio 1
	v_mfma_f32_16x16x32_bf16 v[126:129], v[180:183], v[196:199], 0
	v_mfma_f32_16x16x32_bf16 v[122:125], v[188:191], v[196:199], 0
	v_mfma_f32_16x16x32_bf16 v[118:121], v[180:183], v[218:221], 0
	v_mfma_f32_16x16x32_bf16 v[114:117], v[188:191], v[218:221], 0
	v_mfma_f32_16x16x32_bf16 v[110:113], v[180:183], v[226:229], 0
	v_mfma_f32_16x16x32_bf16 v[106:109], v[188:191], v[226:229], 0
	v_mfma_f32_16x16x32_bf16 v[102:105], v[180:183], v[234:237], 0
	v_mfma_f32_16x16x32_bf16 v[98:101], v[188:191], v[234:237], 0
	v_mfma_f32_16x16x32_bf16 v[126:129], v[184:187], v[214:217], v[126:129]
	v_mfma_f32_16x16x32_bf16 v[122:125], v[192:195], v[214:217], v[122:125]
	v_mfma_f32_16x16x32_bf16 v[118:121], v[184:187], v[222:225], v[118:121]
	v_mfma_f32_16x16x32_bf16 v[114:117], v[192:195], v[222:225], v[114:117]
	v_mfma_f32_16x16x32_bf16 v[110:113], v[184:187], v[230:233], v[110:113]
	v_mfma_f32_16x16x32_bf16 v[106:109], v[192:195], v[230:233], v[106:109]
	v_mfma_f32_16x16x32_bf16 v[102:105], v[184:187], v[238:241], v[102:105]
	v_mfma_f32_16x16x32_bf16 v[98:101], v[192:195], v[238:241], v[98:101]
	s_setprio 0
	s_barrier
	s_add_i32 s64, s64, s2
	v_lshl_add_u64 v[156:157], s[30:31], 0, v[0:1]
	s_mov_b32 m0, s64
	ds_read_b128 v[196:199], v151 offset:16384
	ds_read_b128 v[214:217], v151 offset:17408
	ds_read_b128 v[218:221], v151 offset:18432
	ds_read_b128 v[222:225], v151 offset:19456
	ds_read_b128 v[226:229], v151 offset:20480
	ds_read_b128 v[230:233], v151 offset:21504
	ds_read_b128 v[234:237], v151 offset:22528
	ds_read_b128 v[238:241], v151 offset:23552
	global_load_lds_dwordx4 v[156:157], off
	s_add_i32 m0, s64, 0x2000
	s_add_u32 s64, s30, 0x40000
	v_lshl_add_u64 v[242:243], s[30:31], 0, v[130:131]
	s_addc_u32 s65, s31, 0
	s_add_i32 s66, s66, s2
	global_load_lds_dwordx4 v[242:243], off
	v_lshl_add_u64 v[244:245], s[64:65], 0, v[0:1]
	s_mov_b32 m0, s66
	v_lshl_add_u64 v[246:247], s[34:35], 0, v[132:133]
	global_load_lds_dwordx4 v[244:245], off
	v_lshl_add_u64 v[244:245], s[64:65], 0, v[130:131]
	s_add_i32 m0, s66, 0x2000
	s_nop 0
	global_load_lds_dwordx4 v[244:245], off
	v_lshl_add_u64 v[244:245], s[34:35], 0, v[134:135]
	s_mov_b32 m0, s46
	s_nop 0
	global_load_lds_dwordx4 v[244:245], off
	s_mov_b32 m0, s47
	s_nop 0
	global_load_lds_dwordx4 v[246:247], off
	s_waitcnt vmcnt(8)
	s_waitcnt lgkmcnt(0)
	s_barrier
; #define PG8_STAGE(bufoff, gbase, voff) do { _Pragma("unroll") for (int _i = 0; _i < 2; ++_i) \
;         __builtin_amdgcn_global_load_lds((const unsigned*)((const char*)(gbase) + (voff)[_i]), (PG8_LAS unsigned*)(lds + (bufoff) + ldsw + _i * 8192), 16, 0, 0); } while (0)
; #define PG8_LDA(dst, b, h) do { _Pragma("unroll") for (int m = 0; m < 4; ++m) _Pragma("unroll") for (int k = 0; k < 2; ++k) dst[m][k] = *(const PG8_LAS bf16x8*)(lds + PG8_SA(b, h) + aoff + m * 2048 + k * 1024); } while (0)
; #define PG8_LDB(dst, b, h) do { _Pragma("unroll") for (int n = 0; n < 2; ++n) _Pragma("unroll") for (int k = 0; k < 2; ++k) dst[n][k] = *(const PG8_LAS bf16x8*)(lds + PG8_SB(b, h) + boff + n * 2048 + k * 1024); } while (0)
; #define PG8_MMA(ai, bj, At, Bt) do { __builtin_amdgcn_s_setprio(1); _Pragma("unroll") for (int m = 0; m < 4; ++m) _Pragma("unroll") for (int n = 0; n < 2; ++n) _Pragma("unroll") for (int k = 0; k < 2; ++k) \
;         acc[ai][bj][m][n] = __builtin_amdgcn_mfma_f32_16x16x32_bf16(Bt[n][k], At[m][k], acc[ai][bj][m][n], 0, 0, 0); __builtin_amdgcn_s_setprio(0); } while (0)
; #define PG8_WAIT_V(n) asm volatile("s_waitcnt vmcnt(" #n ")" ::: "memory")
; #define PG8_WAIT_L(n) asm volatile("s_waitcnt lgkmcnt(" #n ")" ::: "memory")
; #define PG8_BAR __builtin_amdgcn_s_barrier()
; #define PG8_SCHED __builtin_amdgcn_sched_barrier(0)
; template <class Epi, class Sched, bool ALIGN_EPI = false, bool SP2 = false>
; __device__ __forceinline__ void gemm_phase(PG8_LAS unsigned char* lds, const Gemm g, const Sched& S, const Epi& E) {
;     ...
;             PG8_WAIT_V(8); PG8_WAIT_L(0); PG8_BAR; PG8_MMA(1, 0, At, B0); PG8_MMA(1, 1, At, B1); PG8_BAR; PG8_SCHED;
;             PG8_LDB(B0, 1, 0); PG8_LDB(B1, 1, 1); PG8_SCHED; PG8_LDA(At, 1, 0); PG8_STAGE(PG8_SA(0, 1), a2 + hstep, voffA);
;             PG8_WAIT_V(8); PG8_WAIT_L(0); PG8_BAR; PG8_MMA(0, 0, At, B0); PG8_MMA(0, 1, At, B1); PG8_BAR; PG8_SCHED;
	s_setprio 1
	s_waitcnt lgkmcnt(0)
	v_mfma_f32_16x16x32_bf16 v[30:33], v[144:147], v[196:199], 0
	v_mfma_f32_16x16x32_bf16 v[26:29], v[172:175], v[196:199], 0
	v_mfma_f32_16x16x32_bf16 v[22:25], v[144:147], v[218:221], 0
	v_mfma_f32_16x16x32_bf16 v[18:21], v[172:175], v[218:221], 0
	v_mfma_f32_16x16x32_bf16 v[14:17], v[144:147], v[226:229], 0
	v_mfma_f32_16x16x32_bf16 v[10:13], v[172:175], v[226:229], 0
	v_mfma_f32_16x16x32_bf16 v[6:9], v[144:147], v[234:237], 0
	v_mfma_f32_16x16x32_bf16 v[2:5], v[172:175], v[234:237], 0
	v_mfma_f32_16x16x32_bf16 v[30:33], v[152:155], v[214:217], v[30:33]
	v_mfma_f32_16x16x32_bf16 v[26:29], v[176:179], v[214:217], v[26:29]
	v_mfma_f32_16x16x32_bf16 v[22:25], v[152:155], v[222:225], v[22:25]
	v_mfma_f32_16x16x32_bf16 v[18:21], v[176:179], v[222:225], v[18:21]
	v_mfma_f32_16x16x32_bf16 v[14:17], v[152:155], v[230:233], v[14:17]
	v_mfma_f32_16x16x32_bf16 v[10:13], v[176:179], v[230:233], v[10:13]
	v_mfma_f32_16x16x32_bf16 v[6:9], v[152:155], v[238:241], v[6:9]
	v_mfma_f32_16x16x32_bf16 v[2:5], v[176:179], v[238:241], v[2:5]
	s_setprio 0
	s_setprio 1
	v_mfma_f32_16x16x32_bf16 v[94:97], v[180:183], v[196:199], 0
	v_mfma_f32_16x16x32_bf16 v[90:93], v[188:191], v[196:199], 0
	v_mfma_f32_16x16x32_bf16 v[86:89], v[180:183], v[218:221], 0
	v_mfma_f32_16x16x32_bf16 v[82:85], v[188:191], v[218:221], 0
	v_mfma_f32_16x16x32_bf16 v[78:81], v[180:183], v[226:229], 0
	v_mfma_f32_16x16x32_bf16 v[74:77], v[188:191], v[226:229], 0
	v_mfma_f32_16x16x32_bf16 v[70:73], v[180:183], v[234:237], 0
	v_mfma_f32_16x16x32_bf16 v[66:69], v[188:191], v[234:237], 0
	v_mfma_f32_16x16x32_bf16 v[94:97], v[184:187], v[214:217], v[94:97]
	v_mfma_f32_16x16x32_bf16 v[90:93], v[192:195], v[214:217], v[90:93]
	v_mfma_f32_16x16x32_bf16 v[86:89], v[184:187], v[222:225], v[86:89]
	v_mfma_f32_16x16x32_bf16 v[82:85], v[192:195], v[222:225], v[82:85]
	v_mfma_f32_16x16x32_bf16 v[78:81], v[184:187], v[230:233], v[78:81]
	v_mfma_f32_16x16x32_bf16 v[74:77], v[192:195], v[230:233], v[74:77]
	v_mfma_f32_16x16x32_bf16 v[70:73], v[184:187], v[238:241], v[70:73]
	v_mfma_f32_16x16x32_bf16 v[66:69], v[192:195], v[238:241], v[66:69]
	s_setprio 0
	s_barrier
	s_add_i32 s64, 0, 0x18000
	v_add_u32_e32 v158, s64, v149
	s_add_i32 s65, 0, 0x1c000
	ds_read_b128 v[144:147], v158
	ds_read_b128 v[152:155], v158 offset:1024
	ds_read_b128 v[172:175], v158 offset:2048
	ds_read_b128 v[176:179], v158 offset:3072
	v_add_u32_e32 v158, s65, v149
	ds_read_b128 v[180:183], v158
	ds_read_b128 v[184:187], v158 offset:1024
	ds_read_b128 v[188:191], v158 offset:2048
	ds_read_b128 v[192:195], v158 offset:3072
	s_add_u32 s34, s34, 0x40000
	s_addc_u32 s35, s35, 0
	s_mov_b32 m0, s48
	v_lshl_add_u64 v[248:249], s[34:35], 0, v[134:135]
	ds_read_b128 v[196:199], v151 offset:32768
	ds_read_b128 v[214:217], v151 offset:33792
	ds_read_b128 v[218:221], v151 offset:34816
	ds_read_b128 v[222:225], v151 offset:35840
	ds_read_b128 v[226:229], v151 offset:36864
	ds_read_b128 v[230:233], v151 offset:37888
	ds_read_b128 v[234:237], v151 offset:38912
	ds_read_b128 v[238:241], v151 offset:39936
	global_load_lds_dwordx4 v[248:249], off
	v_lshl_add_u64 v[248:249], s[34:35], 0, v[132:133]
	s_mov_b32 m0, s49
	s_nop 0
	global_load_lds_dwordx4 v[248:249], off
	s_waitcnt vmcnt(8)
	s_waitcnt lgkmcnt(0)
	s_barrier
	s_setprio 1
	s_waitcnt lgkmcnt(0)
	v_mfma_f32_16x16x32_bf16 v[62:65], v[144:147], v[196:199], v[62:65]
	v_mfma_f32_16x16x32_bf16 v[58:61], v[172:175], v[196:199], v[58:61]
	v_mfma_f32_16x16x32_bf16 v[54:57], v[144:147], v[218:221], v[54:57]
	v_mfma_f32_16x16x32_bf16 v[50:53], v[172:175], v[218:221], v[50:53]
	v_mfma_f32_16x16x32_bf16 v[46:49], v[144:147], v[226:229], v[46:49]
	v_mfma_f32_16x16x32_bf16 v[42:45], v[172:175], v[226:229], v[42:45]
	v_mfma_f32_16x16x32_bf16 v[38:41], v[144:147], v[234:237], v[38:41]
	v_mfma_f32_16x16x32_bf16 v[34:37], v[172:175], v[234:237], v[34:37]
	v_mfma_f32_16x16x32_bf16 v[62:65], v[152:155], v[214:217], v[62:65]
	v_mfma_f32_16x16x32_bf16 v[58:61], v[176:179], v[214:217], v[58:61]
	v_mfma_f32_16x16x32_bf16 v[54:57], v[152:155], v[222:225], v[54:57]
	v_mfma_f32_16x16x32_bf16 v[50:53], v[176:179], v[222:225], v[50:53]
	v_mfma_f32_16x16x32_bf16 v[46:49], v[152:155], v[230:233], v[46:49]
	v_mfma_f32_16x16x32_bf16 v[42:45], v[176:179], v[230:233], v[42:45]
	v_mfma_f32_16x16x32_bf16 v[38:41], v[152:155], v[238:241], v[38:41]
	v_mfma_f32_16x16x32_bf16 v[34:37], v[176:179], v[238:241], v[34:37]
	s_setprio 0
	s_setprio 1
	v_mfma_f32_16x16x32_bf16 v[126:129], v[180:183], v[196:199], v[126:129]
	v_mfma_f32_16x16x32_bf16 v[122:125], v[188:191], v[196:199], v[122:125]
	v_mfma_f32_16x16x32_bf16 v[118:121], v[180:183], v[218:221], v[118:121]
	v_mfma_f32_16x16x32_bf16 v[114:117], v[188:191], v[218:221], v[114:117]
	v_mfma_f32_16x16x32_bf16 v[110:113], v[180:183], v[226:229], v[110:113]
	v_mfma_f32_16x16x32_bf16 v[106:109], v[188:191], v[226:229], v[106:109]
	v_mfma_f32_16x16x32_bf16 v[102:105], v[180:183], v[234:237], v[102:105]
	v_mfma_f32_16x16x32_bf16 v[98:101], v[188:191], v[234:237], v[98:101]
	v_mfma_f32_16x16x32_bf16 v[126:129], v[184:187], v[214:217], v[126:129]
	v_mfma_f32_16x16x32_bf16 v[122:125], v[192:195], v[214:217], v[122:125]
	v_mfma_f32_16x16x32_bf16 v[118:121], v[184:187], v[222:225], v[118:121]
	v_mfma_f32_16x16x32_bf16 v[114:117], v[192:195], v[222:225], v[114:117]
	v_mfma_f32_16x16x32_bf16 v[110:113], v[184:187], v[230:233], v[110:113]
	v_mfma_f32_16x16x32_bf16 v[106:109], v[192:195], v[230:233], v[106:109]
	v_mfma_f32_16x16x32_bf16 v[102:105], v[184:187], v[238:241], v[102:105]
	v_mfma_f32_16x16x32_bf16 v[98:101], v[192:195], v[238:241], v[98:101]
	s_setprio 0
	s_barrier
; #define PG8_STAGE(bufoff, gbase, voff) do { _Pragma("unroll") for (int _i = 0; _i < 2; ++_i) \
;         __builtin_amdgcn_global_load_lds((const unsigned*)((const char*)(gbase) + (voff)[_i]), (PG8_LAS unsigned*)(lds + (bufoff) + ldsw + _i * 8192), 16, 0, 0); } while (0)
; #define PG8_LDA(dst, b, h) do { _Pragma("unroll") for (int m = 0; m < 4; ++m) _Pragma("unroll") for (int k = 0; k < 2; ++k) dst[m][k] = *(const PG8_LAS bf16x8*)(lds + PG8_SA(b, h) + aoff + m * 2048 + k * 1024); } while (0)
; #define PG8_MMA(ai, bj, At, Bt) do { __builtin_amdgcn_s_setprio(1); _Pragma("unroll") for (int m = 0; m < 4; ++m) _Pragma("unroll") for (int n = 0; n < 2; ++n) _Pragma("unroll") for (int k = 0; k < 2; ++k) \
;         acc[ai][bj][m][n] = __builtin_amdgcn_mfma_f32_16x16x32_bf16(Bt[n][k], At[m][k], acc[ai][bj][m][n], 0, 0, 0); __builtin_amdgcn_s_setprio(0); } while (0)
; #define PG8_WAIT_V(n) asm volatile("s_waitcnt vmcnt(" #n ")" ::: "memory")
; #define PG8_WAIT_L(n) asm volatile("s_waitcnt lgkmcnt(" #n ")" ::: "memory")
; #define PG8_BAR __builtin_amdgcn_s_barrier()
; #define PG8_SCHED __builtin_amdgcn_sched_barrier(0)
; template <class Epi, class Sched, bool ALIGN_EPI = false, bool SP2 = false>
; __device__ __forceinline__ void gemm_phase(PG8_LAS unsigned char* lds, const Gemm g, const Sched& S, const Epi& E) {
;     ...
;         for (int t = 0; t < nt; t += 2) {
;             const bool last = (t == nt - 2);
;             const char* a1 = cA + (size_t)(t + 1) * kstep;
;             const char* a2 = last ? nA : cA + (size_t)(t + 2) * kstep; const char* b2 = last ? nB : cB + (size_t)(t + 2) * kstep;
;             const char* a3 = a2 + kstep; const char* b3 = b2 + kstep;
;     ...
;             PG8_LDA(At, 1, 1); PG8_STAGE(PG8_SB(1, 0), b3, voffB); PG8_STAGE(PG8_SB(1, 1), b3 + hstep, voffB); PG8_STAGE(PG8_SA(1, 0), a3, voffA);
;             PG8_WAIT_V(8); PG8_WAIT_L(0); PG8_BAR; PG8_MMA(1, 0, At, B0); PG8_MMA(1, 1, At, B1); PG8_BAR; PG8_SCHED;
	s_add_i32 s34, s64, s2
	v_lshl_add_u64 v[156:157], v[156:157], 0, s[90:91]
	s_mov_b32 m0, s34
	ds_read_b128 v[196:199], v151 offset:49152
	ds_read_b128 v[214:217], v151 offset:50176
	ds_read_b128 v[218:221], v151 offset:51200
	ds_read_b128 v[222:225], v151 offset:52224
	ds_read_b128 v[226:229], v151 offset:53248
	ds_read_b128 v[230:233], v151 offset:54272
	ds_read_b128 v[234:237], v151 offset:55296
	ds_read_b128 v[238:241], v151 offset:56320
	global_load_lds_dwordx4 v[156:157], off
	s_add_i32 m0, s34, 0x2000
	s_add_u32 s30, s30, 0x40080
	v_lshl_add_u64 v[156:157], v[242:243], 0, s[90:91]
	s_addc_u32 s31, s31, 0
	s_add_i32 s34, s65, s2
	global_load_lds_dwordx4 v[156:157], off
	v_lshl_add_u64 v[156:157], s[30:31], 0, v[0:1]
	s_mov_b32 m0, s34
	s_nop 0
	global_load_lds_dwordx4 v[156:157], off
	v_lshl_add_u64 v[156:157], s[30:31], 0, v[130:131]
	s_add_i32 m0, s34, 0x2000
	s_nop 0
	global_load_lds_dwordx4 v[156:157], off
	v_lshl_add_u64 v[156:157], v[244:245], 0, s[90:91]
	s_mov_b32 m0, s52
	s_nop 0
	global_load_lds_dwordx4 v[156:157], off
	v_lshl_add_u64 v[156:157], v[246:247], 0, s[90:91]
	s_mov_b32 m0, s53
	s_nop 0
	global_load_lds_dwordx4 v[156:157], off
	s_waitcnt vmcnt(8)
	s_waitcnt lgkmcnt(0)
	s_barrier
	s_setprio 1
	s_waitcnt lgkmcnt(0)
	v_mfma_f32_16x16x32_bf16 v[30:33], v[144:147], v[196:199], v[30:33]
	v_mfma_f32_16x16x32_bf16 v[26:29], v[172:175], v[196:199], v[26:29]
	v_mfma_f32_16x16x32_bf16 v[22:25], v[144:147], v[218:221], v[22:25]
	v_mfma_f32_16x16x32_bf16 v[18:21], v[172:175], v[218:221], v[18:21]
	v_mfma_f32_16x16x32_bf16 v[14:17], v[144:147], v[226:229], v[14:17]
	v_mfma_f32_16x16x32_bf16 v[10:13], v[172:175], v[226:229], v[10:13]
	v_mfma_f32_16x16x32_bf16 v[6:9], v[144:147], v[234:237], v[6:9]
	v_mfma_f32_16x16x32_bf16 v[2:5], v[172:175], v[234:237], v[2:5]
	v_mfma_f32_16x16x32_bf16 v[30:33], v[152:155], v[214:217], v[30:33]
	v_mfma_f32_16x16x32_bf16 v[26:29], v[176:179], v[214:217], v[26:29]
	v_mfma_f32_16x16x32_bf16 v[22:25], v[152:155], v[222:225], v[22:25]
	v_mfma_f32_16x16x32_bf16 v[18:21], v[176:179], v[222:225], v[18:21]
	v_mfma_f32_16x16x32_bf16 v[14:17], v[152:155], v[230:233], v[14:17]
	v_mfma_f32_16x16x32_bf16 v[10:13], v[176:179], v[230:233], v[10:13]
	v_mfma_f32_16x16x32_bf16 v[6:9], v[152:155], v[238:241], v[6:9]
	v_mfma_f32_16x16x32_bf16 v[2:5], v[176:179], v[238:241], v[2:5]
	s_setprio 0
	s_setprio 1
	v_mfma_f32_16x16x32_bf16 v[94:97], v[180:183], v[196:199], v[94:97]
	v_mfma_f32_16x16x32_bf16 v[90:93], v[188:191], v[196:199], v[90:93]
	v_mfma_f32_16x16x32_bf16 v[86:89], v[180:183], v[218:221], v[86:89]
	v_mfma_f32_16x16x32_bf16 v[82:85], v[188:191], v[218:221], v[82:85]
	v_mfma_f32_16x16x32_bf16 v[78:81], v[180:183], v[226:229], v[78:81]
	v_mfma_f32_16x16x32_bf16 v[74:77], v[188:191], v[226:229], v[74:77]
	v_mfma_f32_16x16x32_bf16 v[70:73], v[180:183], v[234:237], v[70:73]
	v_mfma_f32_16x16x32_bf16 v[66:69], v[188:191], v[234:237], v[66:69]
	v_mfma_f32_16x16x32_bf16 v[94:97], v[184:187], v[214:217], v[94:97]
	v_mfma_f32_16x16x32_bf16 v[90:93], v[192:195], v[214:217], v[90:93]
	v_mfma_f32_16x16x32_bf16 v[86:89], v[184:187], v[222:225], v[86:89]
	v_mfma_f32_16x16x32_bf16 v[82:85], v[192:195], v[222:225], v[82:85]
	v_mfma_f32_16x16x32_bf16 v[78:81], v[184:187], v[230:233], v[78:81]
	v_mfma_f32_16x16x32_bf16 v[74:77], v[192:195], v[230:233], v[74:77]
	v_mfma_f32_16x16x32_bf16 v[70:73], v[184:187], v[238:241], v[70:73]
	v_mfma_f32_16x16x32_bf16 v[66:69], v[192:195], v[238:241], v[66:69]
	s_setprio 0
	s_barrier
	s_add_i32 s63, s63, 2
	s_add_u32 s28, s28, 0x100
	s_addc_u32 s29, s29, 0
	s_add_u32 s61, s61, 0x100
	s_addc_u32 s62, s62, 0

; __device__ __forceinline__ unsigned cvt_pk_bf16(float lo, float hi) { f32x2_cv v = {lo, hi}; bf16x2_cv b = __builtin_convertvector(v, bf16x2_cv); return __builtin_bit_cast(unsigned, b); }
; __device__ __forceinline__ float row_rstd(const float* rsp, int row, int fq) {
;     const f32x4 v = *(const f32x4*)(rsp + (size_t)row * 16 + 4 * fq);
;     float s = (v[0] + v[1]) + (v[2] + v[3]); s += __shfl_xor(s, 16); s += __shfl_xor(s, 32);
;     return rsqrtf(s * (1.0f / 1024.0f) + RMS_EPS);
; }
;     __device__ __forceinline__ void operator()(const f32x4 (&acc)[2][2][4][2], const Unit& u, int wr, int wc, int fr, int fq) const {
;     ...
;         const int t = u.pn / tiles_per_split; bf16_t* base = O + (size_t)t * split_stride; const int colt = (u.pn - t * tiles_per_split) * BM + wc * 32 + 8 * fq;
;         const float sc = (t == 0) ? scale0 : 1.0f;
; #pragma unroll
;         for (int ai = 0; ai < 2; ++ai)
; #pragma unroll
;             for (int m = 0; m < 4; ++m) {
;                 const int row = row0 + ai * HALF + m * 16; const float rs = row_rstd(rsp, row, fq) * sc;
;                 bf16_t* rowp = base + (size_t)row * ldc + colt;
; #pragma unroll
;                 for (int bj = 0; bj < 2; ++bj) {
;                     const f32x4 v0 = acc[ai][bj][m][0] * rs, v1 = acc[ai][bj][m][1] * rs;
;                     u32x4 w; w.x = cvt_pk_bf16(v0[0], v0[1]); w.y = cvt_pk_bf16(v0[2], v0[3]); w.z = cvt_pk_bf16(v1[0], v1[1]); w.w = cvt_pk_bf16(v1[2], v1[3]);
;                     *(u32x4*)(rowp + bj * HALF) = w;
;                 }
;             }
.LBB0_333:
	v_lshl_add_u32 v144, s26, 8, v148
	s_cmp_lg_u32 s59, s51
	s_mov_b64 s[26:27], -1
	s_mov_b64 s[60:61], 0x200000
	s_mov_b64 s[62:63], s[80:81]
	s_cbranch_scc0 .LBB0_335
	v_mov_b32_e32 v145, 0
	v_lshlrev_b64 v[156:157], 6, v[144:145]
	v_lshl_add_u64 v[156:157], v[136:137], 0, v[156:157]
	v_add_co_u32_e32 v218, vcc, 0x2000, v156
	s_nop 1
	v_addc_co_u32_e32 v219, vcc, 0, v157, vcc
	global_load_dwordx4 v[172:175], v[156:157], off
	global_load_dwordx4 v[176:179], v[156:157], off offset:1024
	global_load_dwordx4 v[180:183], v[156:157], off offset:2048
	global_load_dwordx4 v[184:187], v[156:157], off offset:3072
	global_load_dwordx4 v[188:191], v[218:219], off
	global_load_dwordx4 v[192:195], v[218:219], off offset:1024
	global_load_dwordx4 v[196:199], v[218:219], off offset:2048
	global_load_dwordx4 v[214:217], v[218:219], off offset:3072
	s_abs_i32 s21, s59
	s_mul_hi_u32 s26, s21, s58
	s_mul_i32 s27, s26, s50
	s_sub_i32 s21, s21, s27
	s_ashr_i32 s19, s59, 31
	s_add_i32 s27, s26, 1
	s_sub_i32 s28, s21, s50
	s_cmp_ge_u32 s21, s50
	s_cselect_b32 s26, s27, s26
	s_cselect_b32 s21, s28, s21
	s_add_i32 s27, s26, 1
	s_cmp_ge_u32 s21, s50
	s_cselect_b32 s21, s27, s26
	s_xor_b32 s21, s21, s19
	s_sub_i32 s26, s21, s19
	s_ashr_i32 s27, s26, 31
	s_lshl_b64 s[28:29], s[26:27], s55
	s_lshl_b64 s[28:29], s[28:29], 1
	s_add_u32 s28, s0, s28
	s_addc_u32 s29, s1, s29
	s_lshl_b32 s19, s26, s56
	s_sub_i32 s19, s59, s19
	s_cmp_eq_u32 s26, 0
	s_cselect_b64 s[26:27], -1, 0
	s_and_b64 vcc, s[26:27], s[12:13]
	v_xor_b32_e32 v153, 16, v201
	v_xor_b32_e32 v154, 32, v201
	v_cndmask_b32_e32 v152, 1.0, v211, vcc
	v_lshl_or_b32 v146, s19, 8, v150
	s_mov_b64 s[26:27], 0
	v_lshlrev_b32_e32 v153, 2, v153
	v_lshlrev_b32_e32 v154, 2, v154
	v_ashrrev_i32_e32 v147, 31, v146
	v_lshl_add_u64 v[146:147], v[146:147], 1, s[28:29]
	v_mov_b32_e32 v225, 0
	s_waitcnt vmcnt(0)
	v_add_f32_e32 v172, v172, v173
	v_add_f32_e32 v176, v176, v177
	v_add_f32_e32 v180, v180, v181
	v_add_f32_e32 v184, v184, v185
	v_add_f32_e32 v188, v188, v189
	v_add_f32_e32 v192, v192, v193
	v_add_f32_e32 v196, v196, v197
	v_add_f32_e32 v214, v214, v215
	v_add_f32_e32 v174, v174, v175
	v_add_f32_e32 v178, v178, v179
	v_add_f32_e32 v182, v182, v183
	v_add_f32_e32 v186, v186, v187
	v_add_f32_e32 v190, v190, v191
	v_add_f32_e32 v194, v194, v195
	v_add_f32_e32 v198, v198, v199
	v_add_f32_e32 v216, v216, v217
	v_add_f32_e32 v172, v172, v174
	v_add_f32_e32 v176, v176, v178
	v_add_f32_e32 v180, v180, v182
	v_add_f32_e32 v184, v184, v186
	v_add_f32_e32 v188, v188, v190
	v_add_f32_e32 v192, v192, v194
	v_add_f32_e32 v196, v196, v198
	v_add_f32_e32 v214, v214, v216
	ds_bpermute_b32 v173, v153, v172
	ds_bpermute_b32 v177, v153, v176
	ds_bpermute_b32 v181, v153, v180
	ds_bpermute_b32 v185, v153, v184
	ds_bpermute_b32 v189, v153, v188
	ds_bpermute_b32 v193, v153, v192
	ds_bpermute_b32 v197, v153, v196
	ds_bpermute_b32 v215, v153, v214
	s_waitcnt lgkmcnt(0)
	v_add_f32_e32 v172, v172, v173
	v_add_f32_e32 v176, v176, v177
	v_add_f32_e32 v180, v180, v181
	v_add_f32_e32 v184, v184, v185
	v_add_f32_e32 v188, v188, v189
	v_add_f32_e32 v192, v192, v193
	v_add_f32_e32 v196, v196, v197
	v_add_f32_e32 v214, v214, v215
	ds_bpermute_b32 v173, v154, v172
	ds_bpermute_b32 v177, v154, v176
	ds_bpermute_b32 v181, v154, v180
	ds_bpermute_b32 v185, v154, v184
	ds_bpermute_b32 v189, v154, v188
	ds_bpermute_b32 v193, v154, v192
	ds_bpermute_b32 v197, v154, v196
	ds_bpermute_b32 v215, v154, v214
	s_waitcnt lgkmcnt(0)
	v_add_f32_e32 v172, v172, v173
	v_add_f32_e32 v176, v176, v177
	v_add_f32_e32 v180, v180, v181
	v_add_f32_e32 v184, v184, v185
	v_add_f32_e32 v188, v188, v189
	v_add_f32_e32 v192, v192, v193
	v_add_f32_e32 v196, v196, v197
	v_add_f32_e32 v214, v214, v215
	v_fmamk_f32 v172, v172, 0x3a800000, v207
	v_fmamk_f32 v176, v176, 0x3a800000, v207
	v_fmamk_f32 v180, v180, 0x3a800000, v207
	v_fmamk_f32 v184, v184, 0x3a800000, v207
	v_fmamk_f32 v188, v188, 0x3a800000, v207
	v_fmamk_f32 v192, v192, 0x3a800000, v207
	v_fmamk_f32 v196, v196, 0x3a800000, v207
	v_fmamk_f32 v214, v214, 0x3a800000, v207
	v_rsq_f32_e32 v172, v172
	v_rsq_f32_e32 v176, v176
	v_rsq_f32_e32 v180, v180
	v_rsq_f32_e32 v184, v184
	v_rsq_f32_e32 v188, v188
	v_rsq_f32_e32 v192, v192
	v_rsq_f32_e32 v196, v196
	v_rsq_f32_e32 v214, v214
	v_mul_f32_e32 v172, v152, v172
	v_mul_f32_e32 v176, v152, v176
	v_mul_f32_e32 v180, v152, v180
	v_mul_f32_e32 v184, v152, v184
	v_mul_f32_e32 v188, v152, v188
	v_mul_f32_e32 v192, v152, v192
	v_mul_f32_e32 v196, v152, v196
	v_mul_f32_e32 v214, v152, v214
	v_mov_b32_e32 v224, v144
	v_lshlrev_b64 v[222:223], s57, v[224:225]
	v_lshl_add_u64 v[220:221], v[222:223], 1, v[146:147]
	v_pk_mul_f32 v[62:63], v[62:63], v[172:173] op_sel_hi:[1,0]
	v_pk_mul_f32 v[64:65], v[64:65], v[172:173] op_sel_hi:[1,0]
	v_pk_mul_f32 v[58:59], v[58:59], v[172:173] op_sel_hi:[1,0]
	v_pk_mul_f32 v[60:61], v[60:61], v[172:173] op_sel_hi:[1,0]
	v_pk_mul_f32 v[126:127], v[126:127], v[172:173] op_sel_hi:[1,0]
	v_pk_mul_f32 v[128:129], v[128:129], v[172:173] op_sel_hi:[1,0]
	v_pk_mul_f32 v[122:123], v[122:123], v[172:173] op_sel_hi:[1,0]
	v_pk_mul_f32 v[124:125], v[124:125], v[172:173] op_sel_hi:[1,0]
	v_cvt_pk_bf16_f32 v226, v62, v63
	v_cvt_pk_bf16_f32 v227, v64, v65
	v_cvt_pk_bf16_f32 v228, v58, v59
	v_cvt_pk_bf16_f32 v229, v60, v61
	v_cvt_pk_bf16_f32 v230, v126, v127
	v_cvt_pk_bf16_f32 v231, v128, v129
	v_cvt_pk_bf16_f32 v232, v122, v123
	v_cvt_pk_bf16_f32 v233, v124, v125
	global_store_dwordx4 v[220:221], v[226:229], off
	global_store_dwordx4 v[220:221], v[230:233], off offset:256
	v_add_u32_e32 v224, 0x10, v144
	v_lshlrev_b64 v[222:223], s57, v[224:225]
; __device__ __forceinline__ unsigned cvt_pk_bf16(float lo, float hi) { f32x2_cv v = {lo, hi}; bf16x2_cv b = __builtin_convertvector(v, bf16x2_cv); return __builtin_bit_cast(unsigned, b); }
;     __device__ __forceinline__ void operator()(const f32x4 (&acc)[2][2][4][2], const Unit& u, int wr, int wc, int fr, int fq) const {
;     ...
;         for (int ai = 0; ai < 2; ++ai)
; #pragma unroll
;             for (int m = 0; m < 4; ++m) {
;                 const int row = row0 + ai * HALF + m * 16; const float rs = row_rstd(rsp, row, fq) * sc;
;                 bf16_t* rowp = base + (size_t)row * ldc + colt;
; #pragma unroll
;                 for (int bj = 0; bj < 2; ++bj) {
;                     const f32x4 v0 = acc[ai][bj][m][0] * rs, v1 = acc[ai][bj][m][1] * rs;
;                     u32x4 w; w.x = cvt_pk_bf16(v0[0], v0[1]); w.y = cvt_pk_bf16(v0[2], v0[3]); w.z = cvt_pk_bf16(v1[0], v1[1]); w.w = cvt_pk_bf16(v1[2], v1[3]);
;                     *(u32x4*)(rowp + bj * HALF) = w;
;                 }
	v_lshl_add_u64 v[220:221], v[222:223], 1, v[146:147]
	v_pk_mul_f32 v[54:55], v[54:55], v[176:177] op_sel_hi:[1,0]
	v_pk_mul_f32 v[56:57], v[56:57], v[176:177] op_sel_hi:[1,0]
	v_pk_mul_f32 v[50:51], v[50:51], v[176:177] op_sel_hi:[1,0]
	v_pk_mul_f32 v[52:53], v[52:53], v[176:177] op_sel_hi:[1,0]
	v_pk_mul_f32 v[118:119], v[118:119], v[176:177] op_sel_hi:[1,0]
	v_pk_mul_f32 v[120:121], v[120:121], v[176:177] op_sel_hi:[1,0]
	v_pk_mul_f32 v[114:115], v[114:115], v[176:177] op_sel_hi:[1,0]
	v_pk_mul_f32 v[116:117], v[116:117], v[176:177] op_sel_hi:[1,0]
	v_cvt_pk_bf16_f32 v234, v54, v55
	v_cvt_pk_bf16_f32 v235, v56, v57
	v_cvt_pk_bf16_f32 v236, v50, v51
	v_cvt_pk_bf16_f32 v237, v52, v53
	v_cvt_pk_bf16_f32 v238, v118, v119
	v_cvt_pk_bf16_f32 v239, v120, v121
	v_cvt_pk_bf16_f32 v240, v114, v115
	v_cvt_pk_bf16_f32 v241, v116, v117
	global_store_dwordx4 v[220:221], v[234:237], off
	global_store_dwordx4 v[220:221], v[238:241], off offset:256
	v_add_u32_e32 v224, 0x20, v144
	v_lshlrev_b64 v[222:223], s57, v[224:225]
	v_lshl_add_u64 v[220:221], v[222:223], 1, v[146:147]
	v_pk_mul_f32 v[46:47], v[46:47], v[180:181] op_sel_hi:[1,0]
	v_pk_mul_f32 v[48:49], v[48:49], v[180:181] op_sel_hi:[1,0]
	v_pk_mul_f32 v[42:43], v[42:43], v[180:181] op_sel_hi:[1,0]
	v_pk_mul_f32 v[44:45], v[44:45], v[180:181] op_sel_hi:[1,0]
	v_pk_mul_f32 v[110:111], v[110:111], v[180:181] op_sel_hi:[1,0]
	v_pk_mul_f32 v[112:113], v[112:113], v[180:181] op_sel_hi:[1,0]
	v_pk_mul_f32 v[106:107], v[106:107], v[180:181] op_sel_hi:[1,0]
	v_pk_mul_f32 v[108:109], v[108:109], v[180:181] op_sel_hi:[1,0]
	v_cvt_pk_bf16_f32 v226, v46, v47
	v_cvt_pk_bf16_f32 v227, v48, v49
	v_cvt_pk_bf16_f32 v228, v42, v43
	v_cvt_pk_bf16_f32 v229, v44, v45
	v_cvt_pk_bf16_f32 v230, v110, v111
	v_cvt_pk_bf16_f32 v231, v112, v113
	v_cvt_pk_bf16_f32 v232, v106, v107
	v_cvt_pk_bf16_f32 v233, v108, v109
	global_store_dwordx4 v[220:221], v[226:229], off
	global_store_dwordx4 v[220:221], v[230:233], off offset:256
	v_add_u32_e32 v224, 0x30, v144
	v_lshlrev_b64 v[222:223], s57, v[224:225]
	v_lshl_add_u64 v[220:221], v[222:223], 1, v[146:147]
	v_pk_mul_f32 v[38:39], v[38:39], v[184:185] op_sel_hi:[1,0]
	v_pk_mul_f32 v[40:41], v[40:41], v[184:185] op_sel_hi:[1,0]
	v_pk_mul_f32 v[34:35], v[34:35], v[184:185] op_sel_hi:[1,0]
	v_pk_mul_f32 v[36:37], v[36:37], v[184:185] op_sel_hi:[1,0]
	v_pk_mul_f32 v[102:103], v[102:103], v[184:185] op_sel_hi:[1,0]
	v_pk_mul_f32 v[104:105], v[104:105], v[184:185] op_sel_hi:[1,0]
	v_pk_mul_f32 v[98:99], v[98:99], v[184:185] op_sel_hi:[1,0]
	v_pk_mul_f32 v[100:101], v[100:101], v[184:185] op_sel_hi:[1,0]
	v_cvt_pk_bf16_f32 v234, v38, v39
	v_cvt_pk_bf16_f32 v235, v40, v41
	v_cvt_pk_bf16_f32 v236, v34, v35
	v_cvt_pk_bf16_f32 v237, v36, v37
	v_cvt_pk_bf16_f32 v238, v102, v103
	v_cvt_pk_bf16_f32 v239, v104, v105
	v_cvt_pk_bf16_f32 v240, v98, v99
	v_cvt_pk_bf16_f32 v241, v100, v101
	global_store_dwordx4 v[220:221], v[234:237], off
	global_store_dwordx4 v[220:221], v[238:241], off offset:256
	v_add_u32_e32 v224, 0x80, v144
	v_lshlrev_b64 v[222:223], s57, v[224:225]
	v_lshl_add_u64 v[220:221], v[222:223], 1, v[146:147]
	v_pk_mul_f32 v[30:31], v[30:31], v[188:189] op_sel_hi:[1,0]
	v_pk_mul_f32 v[32:33], v[32:33], v[188:189] op_sel_hi:[1,0]
	v_pk_mul_f32 v[26:27], v[26:27], v[188:189] op_sel_hi:[1,0]
	v_pk_mul_f32 v[28:29], v[28:29], v[188:189] op_sel_hi:[1,0]
	v_pk_mul_f32 v[94:95], v[94:95], v[188:189] op_sel_hi:[1,0]
	v_pk_mul_f32 v[96:97], v[96:97], v[188:189] op_sel_hi:[1,0]
	v_pk_mul_f32 v[90:91], v[90:91], v[188:189] op_sel_hi:[1,0]
	v_pk_mul_f32 v[92:93], v[92:93], v[188:189] op_sel_hi:[1,0]
	v_cvt_pk_bf16_f32 v226, v30, v31
	v_cvt_pk_bf16_f32 v227, v32, v33
	v_cvt_pk_bf16_f32 v228, v26, v27
	v_cvt_pk_bf16_f32 v229, v28, v29
	v_cvt_pk_bf16_f32 v230, v94, v95
	v_cvt_pk_bf16_f32 v231, v96, v97
	v_cvt_pk_bf16_f32 v232, v90, v91
	v_cvt_pk_bf16_f32 v233, v92, v93
	global_store_dwordx4 v[220:221], v[226:229], off
	global_store_dwordx4 v[220:221], v[230:233], off offset:256
	v_add_u32_e32 v224, 0x90, v144
	v_lshlrev_b64 v[222:223], s57, v[224:225]
	v_lshl_add_u64 v[220:221], v[222:223], 1, v[146:147]
	v_pk_mul_f32 v[22:23], v[22:23], v[192:193] op_sel_hi:[1,0]
	v_pk_mul_f32 v[24:25], v[24:25], v[192:193] op_sel_hi:[1,0]
	v_pk_mul_f32 v[18:19], v[18:19], v[192:193] op_sel_hi:[1,0]
	v_pk_mul_f32 v[20:21], v[20:21], v[192:193] op_sel_hi:[1,0]
	v_pk_mul_f32 v[86:87], v[86:87], v[192:193] op_sel_hi:[1,0]
	v_pk_mul_f32 v[88:89], v[88:89], v[192:193] op_sel_hi:[1,0]
	v_pk_mul_f32 v[82:83], v[82:83], v[192:193] op_sel_hi:[1,0]
	v_pk_mul_f32 v[84:85], v[84:85], v[192:193] op_sel_hi:[1,0]
	v_cvt_pk_bf16_f32 v234, v22, v23
	v_cvt_pk_bf16_f32 v235, v24, v25
	v_cvt_pk_bf16_f32 v236, v18, v19
	v_cvt_pk_bf16_f32 v237, v20, v21
	v_cvt_pk_bf16_f32 v238, v86, v87
	v_cvt_pk_bf16_f32 v239, v88, v89
	v_cvt_pk_bf16_f32 v240, v82, v83
	v_cvt_pk_bf16_f32 v241, v84, v85
	global_store_dwordx4 v[220:221], v[234:237], off
	global_store_dwordx4 v[220:221], v[238:241], off offset:256
	v_add_u32_e32 v224, 0xa0, v144
	v_lshlrev_b64 v[222:223], s57, v[224:225]
	v_lshl_add_u64 v[220:221], v[222:223], 1, v[146:147]
	v_pk_mul_f32 v[14:15], v[14:15], v[196:197] op_sel_hi:[1,0]
	v_pk_mul_f32 v[16:17], v[16:17], v[196:197] op_sel_hi:[1,0]
	v_pk_mul_f32 v[10:11], v[10:11], v[196:197] op_sel_hi:[1,0]
	v_pk_mul_f32 v[12:13], v[12:13], v[196:197] op_sel_hi:[1,0]
	v_pk_mul_f32 v[78:79], v[78:79], v[196:197] op_sel_hi:[1,0]
	v_pk_mul_f32 v[80:81], v[80:81], v[196:197] op_sel_hi:[1,0]
	v_pk_mul_f32 v[74:75], v[74:75], v[196:197] op_sel_hi:[1,0]
	v_pk_mul_f32 v[76:77], v[76:77], v[196:197] op_sel_hi:[1,0]
	v_cvt_pk_bf16_f32 v226, v14, v15
	v_cvt_pk_bf16_f32 v227, v16, v17
	v_cvt_pk_bf16_f32 v228, v10, v11
	v_cvt_pk_bf16_f32 v229, v12, v13
	v_cvt_pk_bf16_f32 v230, v78, v79
	v_cvt_pk_bf16_f32 v231, v80, v81
	v_cvt_pk_bf16_f32 v232, v74, v75
	v_cvt_pk_bf16_f32 v233, v76, v77
	global_store_dwordx4 v[220:221], v[226:229], off
	global_store_dwordx4 v[220:221], v[230:233], off offset:256
	v_add_u32_e32 v224, 0xb0, v144
	v_lshlrev_b64 v[222:223], s57, v[224:225]
	v_lshl_add_u64 v[220:221], v[222:223], 1, v[146:147]
	v_pk_mul_f32 v[6:7], v[6:7], v[214:215] op_sel_hi:[1,0]
	v_pk_mul_f32 v[8:9], v[8:9], v[214:215] op_sel_hi:[1,0]
	v_pk_mul_f32 v[2:3], v[2:3], v[214:215] op_sel_hi:[1,0]
	v_pk_mul_f32 v[4:5], v[4:5], v[214:215] op_sel_hi:[1,0]
	v_pk_mul_f32 v[70:71], v[70:71], v[214:215] op_sel_hi:[1,0]
	v_pk_mul_f32 v[72:73], v[72:73], v[214:215] op_sel_hi:[1,0]
	v_pk_mul_f32 v[66:67], v[66:67], v[214:215] op_sel_hi:[1,0]
	v_pk_mul_f32 v[68:69], v[68:69], v[214:215] op_sel_hi:[1,0]
	v_cvt_pk_bf16_f32 v234, v6, v7
	v_cvt_pk_bf16_f32 v235, v8, v9
	v_cvt_pk_bf16_f32 v236, v2, v3
	v_cvt_pk_bf16_f32 v237, v4, v5
	v_cvt_pk_bf16_f32 v238, v70, v71
	v_cvt_pk_bf16_f32 v239, v72, v73
	v_cvt_pk_bf16_f32 v240, v66, v67
	v_cvt_pk_bf16_f32 v241, v68, v69
	global_store_dwordx4 v[220:221], v[234:237], off
	global_store_dwordx4 v[220:221], v[238:241], off offset:256

; #define PG8_STAGE(bufoff, gbase, voff) do { _Pragma("unroll") for (int _i = 0; _i < 2; ++_i) \
;         __builtin_amdgcn_global_load_lds((const unsigned*)((const char*)(gbase) + (voff)[_i]), (PG8_LAS unsigned*)(lds + (bufoff) + ldsw + _i * 8192), 16, 0, 0); } while (0)
; #define PG8_LDA(dst, b, h) do { _Pragma("unroll") for (int m = 0; m < 4; ++m) _Pragma("unroll") for (int k = 0; k < 2; ++k) dst[m][k] = *(const PG8_LAS bf16x8*)(lds + PG8_SA(b, h) + aoff + m * 2048 + k * 1024); } while (0)
; #define PG8_LDB(dst, b, h) do { _Pragma("unroll") for (int n = 0; n < 2; ++n) _Pragma("unroll") for (int k = 0; k < 2; ++k) dst[n][k] = *(const PG8_LAS bf16x8*)(lds + PG8_SB(b, h) + boff + n * 2048 + k * 1024); } while (0)
; #define PG8_MMA(ai, bj, At, Bt) do { __builtin_amdgcn_s_setprio(1); _Pragma("unroll") for (int m = 0; m < 4; ++m) _Pragma("unroll") for (int n = 0; n < 2; ++n) _Pragma("unroll") for (int k = 0; k < 2; ++k) \
;         acc[ai][bj][m][n] = __builtin_amdgcn_mfma_f32_16x16x32_bf16(Bt[n][k], At[m][k], acc[ai][bj][m][n], 0, 0, 0); __builtin_amdgcn_s_setprio(0); } while (0)
; #define PG8_WAIT_V(n) asm volatile("s_waitcnt vmcnt(" #n ")" ::: "memory")
; #define PG8_WAIT_L(n) asm volatile("s_waitcnt lgkmcnt(" #n ")" ::: "memory")
; #define PG8_BAR __builtin_amdgcn_s_barrier()
; #define PG8_SCHED __builtin_amdgcn_sched_barrier(0)
; template <class Epi, class Sched, bool ALIGN_EPI = false, bool SP2 = false>
; __device__ __forceinline__ void gemm_phase(PG8_LAS unsigned char* lds, const Gemm g, const Sched& S, const Epi& E) {
;     ...
;     f32x4 acc[2][2][4][2];
; #pragma unroll
;     for (int a = 0; a < 2; ++a)
; #pragma unroll
;         for (int b = 0; b < 2; ++b)
; #pragma unroll
;             for (int m = 0; m < 4; ++m)
; #pragma unroll
;                 for (int n = 0; n < 2; ++n) acc[a][b][m][n] = (f32x4){0.f, 0.f, 0.f, 0.f};
;     ...
;             PG8_LDB(B0, 0, 0); PG8_LDB(B1, 0, 1); PG8_SCHED; PG8_LDA(At, 0, 0); PG8_STAGE(PG8_SA(1, 1), a1 + hstep, voffA);
;             PG8_WAIT_V(8); PG8_WAIT_L(0); PG8_BAR; PG8_MMA(0, 0, At, B0); PG8_MMA(0, 1, At, B1); PG8_BAR; PG8_SCHED;
;             PG8_LDA(At, 0, 1); PG8_STAGE(PG8_SB(0, 0), b2, voffB); PG8_STAGE(PG8_SB(0, 1), b2 + hstep, voffB); PG8_STAGE(PG8_SA(0, 0), a2, voffA);
;             PG8_WAIT_V(8); PG8_WAIT_L(0); PG8_BAR; PG8_MMA(1, 0, At, B0); PG8_MMA(1, 1, At, B1); PG8_BAR; PG8_SCHED;
.LBB0_458:
	s_add_u32 s47, s20, 0x100
	s_addc_u32 s48, s21, 0
	s_mov_b32 s49, -2
	s_waitcnt lgkmcnt(0)
	s_waitcnt vmcnt(0)
	s_add_u32 s20, s18, 0x100
	s_addc_u32 s21, s19, 0
	s_add_i32 s50, 0, 0x10000
	s_cmp_eq_u32 s49, 40
	s_cselect_b32 s25, s9, s21
	s_cselect_b32 s24, s8, s20
	s_cselect_b32 s23, s17, s48
	s_cselect_b32 s22, s16, s47
	s_add_i32 s51, 0, 0x14000
	v_add_u32_e32 v142, s50, v165
	v_add_u32_e32 v182, s51, v165
	ds_read_b128 v[130:133], v142
	ds_read_b128 v[134:137], v142 offset:1024
	ds_read_b128 v[138:141], v142 offset:2048
	ds_read_b128 v[142:145], v142 offset:3072
	ds_read_b128 v[146:149], v182
	ds_read_b128 v[150:153], v182 offset:1024
	ds_read_b128 v[154:157], v182 offset:2048
	ds_read_b128 v[182:185], v182 offset:3072
	v_lshl_add_u64 v[198:199], s[18:19], 0, v[178:179]
	s_add_i32 m0, s28, 0xc000
	ds_read_b128 v[186:189], v214
	ds_read_b128 v[190:193], v214 offset:1024
	ds_read_b128 v[194:197], v214 offset:2048
	ds_read_b128 v[216:219], v214 offset:3072
	ds_read_b128 v[220:223], v214 offset:4096
	ds_read_b128 v[224:227], v214 offset:5120
	ds_read_b128 v[228:231], v214 offset:6144
	ds_read_b128 v[232:235], v214 offset:7168
	global_load_lds_dwordx4 v[198:199], off
	v_lshl_add_u64 v[198:199], s[18:19], 0, v[180:181]
	s_add_i32 m0, s28, 0xe000
	s_nop 0
	global_load_lds_dwordx4 v[198:199], off
	s_waitcnt vmcnt(8)
	s_waitcnt lgkmcnt(0)
	s_barrier
	s_setprio 1
	s_waitcnt lgkmcnt(0)
	v_mfma_f32_16x16x32_bf16 v[126:129], v[130:133], v[186:189], 0
	v_mfma_f32_16x16x32_bf16 v[122:125], v[138:141], v[186:189], 0
	v_mfma_f32_16x16x32_bf16 v[110:113], v[130:133], v[194:197], 0
	v_mfma_f32_16x16x32_bf16 v[106:109], v[138:141], v[194:197], 0
	v_mfma_f32_16x16x32_bf16 v[94:97], v[130:133], v[220:223], 0
	v_mfma_f32_16x16x32_bf16 v[90:93], v[138:141], v[220:223], 0
	v_mfma_f32_16x16x32_bf16 v[78:81], v[130:133], v[228:231], 0
	v_mfma_f32_16x16x32_bf16 v[74:77], v[138:141], v[228:231], 0
	v_mfma_f32_16x16x32_bf16 v[126:129], v[134:137], v[190:193], v[126:129]
	v_mfma_f32_16x16x32_bf16 v[122:125], v[142:145], v[190:193], v[122:125]
	v_mfma_f32_16x16x32_bf16 v[110:113], v[134:137], v[216:219], v[110:113]
	v_mfma_f32_16x16x32_bf16 v[106:109], v[142:145], v[216:219], v[106:109]
	v_mfma_f32_16x16x32_bf16 v[94:97], v[134:137], v[224:227], v[94:97]
	v_mfma_f32_16x16x32_bf16 v[90:93], v[142:145], v[224:227], v[90:93]
	v_mfma_f32_16x16x32_bf16 v[78:81], v[134:137], v[232:235], v[78:81]
	v_mfma_f32_16x16x32_bf16 v[74:77], v[142:145], v[232:235], v[74:77]
	s_setprio 0
	s_setprio 1
	v_mfma_f32_16x16x32_bf16 v[118:121], v[146:149], v[186:189], 0
	v_mfma_f32_16x16x32_bf16 v[114:117], v[154:157], v[186:189], 0
	v_mfma_f32_16x16x32_bf16 v[102:105], v[146:149], v[194:197], 0
	v_mfma_f32_16x16x32_bf16 v[98:101], v[154:157], v[194:197], 0
	v_mfma_f32_16x16x32_bf16 v[86:89], v[146:149], v[220:223], 0
	v_mfma_f32_16x16x32_bf16 v[82:85], v[154:157], v[220:223], 0
	v_mfma_f32_16x16x32_bf16 v[70:73], v[146:149], v[228:231], 0
	v_mfma_f32_16x16x32_bf16 v[66:69], v[154:157], v[228:231], 0
	v_mfma_f32_16x16x32_bf16 v[118:121], v[150:153], v[190:193], v[118:121]
	v_mfma_f32_16x16x32_bf16 v[114:117], v[182:185], v[190:193], v[114:117]
	v_mfma_f32_16x16x32_bf16 v[102:105], v[150:153], v[216:219], v[102:105]
	v_mfma_f32_16x16x32_bf16 v[98:101], v[182:185], v[216:219], v[98:101]
	v_mfma_f32_16x16x32_bf16 v[86:89], v[150:153], v[224:227], v[86:89]
	v_mfma_f32_16x16x32_bf16 v[82:85], v[182:185], v[224:227], v[82:85]
	v_mfma_f32_16x16x32_bf16 v[70:73], v[150:153], v[232:235], v[70:73]
	v_mfma_f32_16x16x32_bf16 v[66:69], v[182:185], v[232:235], v[66:69]
	s_setprio 0
	s_barrier
	s_add_i32 s18, s50, s2
	v_lshl_add_u64 v[198:199], s[22:23], 0, v[0:1]
	s_mov_b32 m0, s18
	ds_read_b128 v[186:189], v214 offset:16384
	ds_read_b128 v[190:193], v214 offset:17408
	ds_read_b128 v[194:197], v214 offset:18432
	ds_read_b128 v[216:219], v214 offset:19456
	ds_read_b128 v[220:223], v214 offset:20480
	ds_read_b128 v[224:227], v214 offset:21504
	ds_read_b128 v[228:231], v214 offset:22528
	ds_read_b128 v[232:235], v214 offset:23552
	global_load_lds_dwordx4 v[198:199], off
	s_add_i32 m0, s18, 0x2000
	s_add_u32 s18, s22, 0xb0000
	v_lshl_add_u64 v[236:237], s[22:23], 0, v[172:173]
	s_addc_u32 s19, s23, 0
	s_add_i32 s50, s51, s2
	global_load_lds_dwordx4 v[236:237], off
	v_lshl_add_u64 v[238:239], s[18:19], 0, v[0:1]
	s_mov_b32 m0, s50
	v_lshl_add_u64 v[240:241], s[24:25], 0, v[174:175]
	global_load_lds_dwordx4 v[238:239], off
	v_lshl_add_u64 v[238:239], s[18:19], 0, v[172:173]
	s_add_i32 m0, s50, 0x2000
	s_nop 0
	global_load_lds_dwordx4 v[238:239], off
	v_lshl_add_u64 v[238:239], s[24:25], 0, v[176:177]
	s_mov_b32 m0, s28
	s_nop 0
	global_load_lds_dwordx4 v[238:239], off
	s_mov_b32 m0, s29
	s_nop 0
	global_load_lds_dwordx4 v[240:241], off
	s_waitcnt vmcnt(8)
	s_waitcnt lgkmcnt(0)
	s_barrier
; #define PG8_STAGE(bufoff, gbase, voff) do { _Pragma("unroll") for (int _i = 0; _i < 2; ++_i) \
;         __builtin_amdgcn_global_load_lds((const unsigned*)((const char*)(gbase) + (voff)[_i]), (PG8_LAS unsigned*)(lds + (bufoff) + ldsw + _i * 8192), 16, 0, 0); } while (0)
; #define PG8_LDA(dst, b, h) do { _Pragma("unroll") for (int m = 0; m < 4; ++m) _Pragma("unroll") for (int k = 0; k < 2; ++k) dst[m][k] = *(const PG8_LAS bf16x8*)(lds + PG8_SA(b, h) + aoff + m * 2048 + k * 1024); } while (0)
; #define PG8_LDB(dst, b, h) do { _Pragma("unroll") for (int n = 0; n < 2; ++n) _Pragma("unroll") for (int k = 0; k < 2; ++k) dst[n][k] = *(const PG8_LAS bf16x8*)(lds + PG8_SB(b, h) + boff + n * 2048 + k * 1024); } while (0)
; #define PG8_MMA(ai, bj, At, Bt) do { __builtin_amdgcn_s_setprio(1); _Pragma("unroll") for (int m = 0; m < 4; ++m) _Pragma("unroll") for (int n = 0; n < 2; ++n) _Pragma("unroll") for (int k = 0; k < 2; ++k) \
;         acc[ai][bj][m][n] = __builtin_amdgcn_mfma_f32_16x16x32_bf16(Bt[n][k], At[m][k], acc[ai][bj][m][n], 0, 0, 0); __builtin_amdgcn_s_setprio(0); } while (0)
; #define PG8_WAIT_V(n) asm volatile("s_waitcnt vmcnt(" #n ")" ::: "memory")
; #define PG8_WAIT_L(n) asm volatile("s_waitcnt lgkmcnt(" #n ")" ::: "memory")
; #define PG8_BAR __builtin_amdgcn_s_barrier()
; #define PG8_SCHED __builtin_amdgcn_sched_barrier(0)
; template <class Epi, class Sched, bool ALIGN_EPI = false, bool SP2 = false>
; __device__ __forceinline__ void gemm_phase(PG8_LAS unsigned char* lds, const Gemm g, const Sched& S, const Epi& E) {
;     ...
;             PG8_WAIT_V(8); PG8_WAIT_L(0); PG8_BAR; PG8_MMA(1, 0, At, B0); PG8_MMA(1, 1, At, B1); PG8_BAR; PG8_SCHED;
;             PG8_LDB(B0, 1, 0); PG8_LDB(B1, 1, 1); PG8_SCHED; PG8_LDA(At, 1, 0); PG8_STAGE(PG8_SA(0, 1), a2 + hstep, voffA);
;             PG8_WAIT_V(8); PG8_WAIT_L(0); PG8_BAR; PG8_MMA(0, 0, At, B0); PG8_MMA(0, 1, At, B1); PG8_BAR; PG8_SCHED;
	s_setprio 1
	s_waitcnt lgkmcnt(0)
	v_mfma_f32_16x16x32_bf16 v[62:65], v[130:133], v[186:189], 0
	v_mfma_f32_16x16x32_bf16 v[58:61], v[138:141], v[186:189], 0
	v_mfma_f32_16x16x32_bf16 v[46:49], v[130:133], v[194:197], 0
	v_mfma_f32_16x16x32_bf16 v[42:45], v[138:141], v[194:197], 0
	v_mfma_f32_16x16x32_bf16 v[30:33], v[130:133], v[220:223], 0
	v_mfma_f32_16x16x32_bf16 v[26:29], v[138:141], v[220:223], 0
	v_mfma_f32_16x16x32_bf16 v[14:17], v[130:133], v[228:231], 0
	v_mfma_f32_16x16x32_bf16 v[10:13], v[138:141], v[228:231], 0
	v_mfma_f32_16x16x32_bf16 v[62:65], v[134:137], v[190:193], v[62:65]
	v_mfma_f32_16x16x32_bf16 v[58:61], v[142:145], v[190:193], v[58:61]
	v_mfma_f32_16x16x32_bf16 v[46:49], v[134:137], v[216:219], v[46:49]
	v_mfma_f32_16x16x32_bf16 v[42:45], v[142:145], v[216:219], v[42:45]
	v_mfma_f32_16x16x32_bf16 v[30:33], v[134:137], v[224:227], v[30:33]
	v_mfma_f32_16x16x32_bf16 v[26:29], v[142:145], v[224:227], v[26:29]
	v_mfma_f32_16x16x32_bf16 v[14:17], v[134:137], v[232:235], v[14:17]
	v_mfma_f32_16x16x32_bf16 v[10:13], v[142:145], v[232:235], v[10:13]
	s_setprio 0
	s_setprio 1
	v_mfma_f32_16x16x32_bf16 v[54:57], v[146:149], v[186:189], 0
	v_mfma_f32_16x16x32_bf16 v[50:53], v[154:157], v[186:189], 0
	v_mfma_f32_16x16x32_bf16 v[38:41], v[146:149], v[194:197], 0
	v_mfma_f32_16x16x32_bf16 v[34:37], v[154:157], v[194:197], 0
	v_mfma_f32_16x16x32_bf16 v[22:25], v[146:149], v[220:223], 0
	v_mfma_f32_16x16x32_bf16 v[18:21], v[154:157], v[220:223], 0
	v_mfma_f32_16x16x32_bf16 v[6:9], v[146:149], v[228:231], 0
	v_mfma_f32_16x16x32_bf16 v[2:5], v[154:157], v[228:231], 0
	v_mfma_f32_16x16x32_bf16 v[54:57], v[150:153], v[190:193], v[54:57]
	v_mfma_f32_16x16x32_bf16 v[50:53], v[182:185], v[190:193], v[50:53]
	v_mfma_f32_16x16x32_bf16 v[38:41], v[150:153], v[216:219], v[38:41]
	v_mfma_f32_16x16x32_bf16 v[34:37], v[182:185], v[216:219], v[34:37]
	v_mfma_f32_16x16x32_bf16 v[22:25], v[150:153], v[224:227], v[22:25]
	v_mfma_f32_16x16x32_bf16 v[18:21], v[182:185], v[224:227], v[18:21]
	v_mfma_f32_16x16x32_bf16 v[6:9], v[150:153], v[232:235], v[6:9]
	v_mfma_f32_16x16x32_bf16 v[2:5], v[182:185], v[232:235], v[2:5]
	s_setprio 0
	s_barrier
	s_add_i32 s50, 0, 0x18000
	s_add_i32 s51, 0, 0x1c000
	v_add_u32_e32 v142, s50, v165
	v_add_u32_e32 v182, s51, v165
	ds_read_b128 v[130:133], v142
	ds_read_b128 v[134:137], v142 offset:1024
	ds_read_b128 v[138:141], v142 offset:2048
	ds_read_b128 v[142:145], v142 offset:3072
	ds_read_b128 v[146:149], v182
	ds_read_b128 v[150:153], v182 offset:1024
	ds_read_b128 v[154:157], v182 offset:2048
	ds_read_b128 v[182:185], v182 offset:3072
	s_add_u32 s18, s24, 0xb0000
	s_addc_u32 s19, s25, 0
	s_mov_b32 m0, s30
	v_lshl_add_u64 v[242:243], s[18:19], 0, v[176:177]
	ds_read_b128 v[186:189], v214 offset:32768
	ds_read_b128 v[190:193], v214 offset:33792
	ds_read_b128 v[194:197], v214 offset:34816
	ds_read_b128 v[216:219], v214 offset:35840
	ds_read_b128 v[220:223], v214 offset:36864
	ds_read_b128 v[224:227], v214 offset:37888
	ds_read_b128 v[228:231], v214 offset:38912
	ds_read_b128 v[232:235], v214 offset:39936
	global_load_lds_dwordx4 v[242:243], off
	v_lshl_add_u64 v[242:243], s[18:19], 0, v[174:175]
	s_mov_b32 m0, s31
	s_nop 0
	global_load_lds_dwordx4 v[242:243], off
	s_waitcnt vmcnt(8)
	s_waitcnt lgkmcnt(0)
	s_barrier
	s_setprio 1
	s_waitcnt lgkmcnt(0)
	v_mfma_f32_16x16x32_bf16 v[126:129], v[130:133], v[186:189], v[126:129]
	v_mfma_f32_16x16x32_bf16 v[122:125], v[138:141], v[186:189], v[122:125]
	v_mfma_f32_16x16x32_bf16 v[110:113], v[130:133], v[194:197], v[110:113]
	v_mfma_f32_16x16x32_bf16 v[106:109], v[138:141], v[194:197], v[106:109]
	v_mfma_f32_16x16x32_bf16 v[94:97], v[130:133], v[220:223], v[94:97]
	v_mfma_f32_16x16x32_bf16 v[90:93], v[138:141], v[220:223], v[90:93]
	v_mfma_f32_16x16x32_bf16 v[78:81], v[130:133], v[228:231], v[78:81]
	v_mfma_f32_16x16x32_bf16 v[74:77], v[138:141], v[228:231], v[74:77]
	v_mfma_f32_16x16x32_bf16 v[126:129], v[134:137], v[190:193], v[126:129]
	v_mfma_f32_16x16x32_bf16 v[122:125], v[142:145], v[190:193], v[122:125]
	v_mfma_f32_16x16x32_bf16 v[110:113], v[134:137], v[216:219], v[110:113]
	v_mfma_f32_16x16x32_bf16 v[106:109], v[142:145], v[216:219], v[106:109]
	v_mfma_f32_16x16x32_bf16 v[94:97], v[134:137], v[224:227], v[94:97]
	v_mfma_f32_16x16x32_bf16 v[90:93], v[142:145], v[224:227], v[90:93]
	v_mfma_f32_16x16x32_bf16 v[78:81], v[134:137], v[232:235], v[78:81]
	v_mfma_f32_16x16x32_bf16 v[74:77], v[142:145], v[232:235], v[74:77]
	s_setprio 0
	s_setprio 1
	v_mfma_f32_16x16x32_bf16 v[118:121], v[146:149], v[186:189], v[118:121]
	v_mfma_f32_16x16x32_bf16 v[114:117], v[154:157], v[186:189], v[114:117]
	v_mfma_f32_16x16x32_bf16 v[102:105], v[146:149], v[194:197], v[102:105]
	v_mfma_f32_16x16x32_bf16 v[98:101], v[154:157], v[194:197], v[98:101]
	v_mfma_f32_16x16x32_bf16 v[86:89], v[146:149], v[220:223], v[86:89]
	v_mfma_f32_16x16x32_bf16 v[82:85], v[154:157], v[220:223], v[82:85]
	v_mfma_f32_16x16x32_bf16 v[70:73], v[146:149], v[228:231], v[70:73]
	v_mfma_f32_16x16x32_bf16 v[66:69], v[154:157], v[228:231], v[66:69]
	v_mfma_f32_16x16x32_bf16 v[118:121], v[150:153], v[190:193], v[118:121]
	v_mfma_f32_16x16x32_bf16 v[114:117], v[182:185], v[190:193], v[114:117]
	v_mfma_f32_16x16x32_bf16 v[102:105], v[150:153], v[216:219], v[102:105]
	v_mfma_f32_16x16x32_bf16 v[98:101], v[182:185], v[216:219], v[98:101]
	v_mfma_f32_16x16x32_bf16 v[86:89], v[150:153], v[224:227], v[86:89]
	v_mfma_f32_16x16x32_bf16 v[82:85], v[182:185], v[224:227], v[82:85]
	v_mfma_f32_16x16x32_bf16 v[70:73], v[150:153], v[232:235], v[70:73]
	v_mfma_f32_16x16x32_bf16 v[66:69], v[182:185], v[232:235], v[66:69]
	s_setprio 0
	s_barrier
; #define PG8_STAGE(bufoff, gbase, voff) do { _Pragma("unroll") for (int _i = 0; _i < 2; ++_i) \
;         __builtin_amdgcn_global_load_lds((const unsigned*)((const char*)(gbase) + (voff)[_i]), (PG8_LAS unsigned*)(lds + (bufoff) + ldsw + _i * 8192), 16, 0, 0); } while (0)
; #define PG8_LDA(dst, b, h) do { _Pragma("unroll") for (int m = 0; m < 4; ++m) _Pragma("unroll") for (int k = 0; k < 2; ++k) dst[m][k] = *(const PG8_LAS bf16x8*)(lds + PG8_SA(b, h) + aoff + m * 2048 + k * 1024); } while (0)
; #define PG8_MMA(ai, bj, At, Bt) do { __builtin_amdgcn_s_setprio(1); _Pragma("unroll") for (int m = 0; m < 4; ++m) _Pragma("unroll") for (int n = 0; n < 2; ++n) _Pragma("unroll") for (int k = 0; k < 2; ++k) \
;         acc[ai][bj][m][n] = __builtin_amdgcn_mfma_f32_16x16x32_bf16(Bt[n][k], At[m][k], acc[ai][bj][m][n], 0, 0, 0); __builtin_amdgcn_s_setprio(0); } while (0)
; #define PG8_WAIT_V(n) asm volatile("s_waitcnt vmcnt(" #n ")" ::: "memory")
; #define PG8_WAIT_L(n) asm volatile("s_waitcnt lgkmcnt(" #n ")" ::: "memory")
; #define PG8_BAR __builtin_amdgcn_s_barrier()
; #define PG8_SCHED __builtin_amdgcn_sched_barrier(0)
; template <class Epi, class Sched, bool ALIGN_EPI = false, bool SP2 = false>
; __device__ __forceinline__ void gemm_phase(PG8_LAS unsigned char* lds, const Gemm g, const Sched& S, const Epi& E) {
;     ...
;         for (int t = 0; t < nt; t += 2) {
;             const bool last = (t == nt - 2);
;             const char* a1 = cA + (size_t)(t + 1) * kstep;
;             const char* a2 = last ? nA : cA + (size_t)(t + 2) * kstep; const char* b2 = last ? nB : cB + (size_t)(t + 2) * kstep;
;             const char* a3 = a2 + kstep; const char* b3 = b2 + kstep;
;     ...
;             PG8_LDA(At, 1, 1); PG8_STAGE(PG8_SB(1, 0), b3, voffB); PG8_STAGE(PG8_SB(1, 1), b3 + hstep, voffB); PG8_STAGE(PG8_SA(1, 0), a3, voffA);
;             PG8_WAIT_V(8); PG8_WAIT_L(0); PG8_BAR; PG8_MMA(1, 0, At, B0); PG8_MMA(1, 1, At, B1); PG8_BAR; PG8_SCHED;
	s_add_i32 s18, s50, s2
	v_lshl_add_u64 v[198:199], v[198:199], 0, s[90:91]
	s_mov_b32 m0, s18
	ds_read_b128 v[186:189], v214 offset:49152
	ds_read_b128 v[190:193], v214 offset:50176
	ds_read_b128 v[194:197], v214 offset:51200
	ds_read_b128 v[216:219], v214 offset:52224
	ds_read_b128 v[220:223], v214 offset:53248
	ds_read_b128 v[224:227], v214 offset:54272
	ds_read_b128 v[228:231], v214 offset:55296
	ds_read_b128 v[232:235], v214 offset:56320
	global_load_lds_dwordx4 v[198:199], off
	s_add_i32 m0, s18, 0x2000
	s_add_u32 s18, s22, 0xb0080
	v_lshl_add_u64 v[198:199], v[236:237], 0, s[90:91]
	s_addc_u32 s19, s23, 0
	s_add_i32 s22, s51, s2
	global_load_lds_dwordx4 v[198:199], off
	v_lshl_add_u64 v[198:199], s[18:19], 0, v[0:1]
	s_mov_b32 m0, s22
	s_nop 0
	global_load_lds_dwordx4 v[198:199], off
	v_lshl_add_u64 v[198:199], s[18:19], 0, v[172:173]
	s_add_i32 m0, s22, 0x2000
	s_nop 0
	global_load_lds_dwordx4 v[198:199], off
	v_lshl_add_u64 v[198:199], v[238:239], 0, s[90:91]
	s_mov_b32 m0, s35
	s_nop 0
	global_load_lds_dwordx4 v[198:199], off
	v_lshl_add_u64 v[198:199], v[240:241], 0, s[90:91]
	s_mov_b32 m0, s37
	s_nop 0
	global_load_lds_dwordx4 v[198:199], off
	s_waitcnt vmcnt(8)
	s_waitcnt lgkmcnt(0)
	s_barrier
	s_setprio 1
	s_waitcnt lgkmcnt(0)
	v_mfma_f32_16x16x32_bf16 v[62:65], v[130:133], v[186:189], v[62:65]
	v_mfma_f32_16x16x32_bf16 v[58:61], v[138:141], v[186:189], v[58:61]
	v_mfma_f32_16x16x32_bf16 v[46:49], v[130:133], v[194:197], v[46:49]
	v_mfma_f32_16x16x32_bf16 v[42:45], v[138:141], v[194:197], v[42:45]
	v_mfma_f32_16x16x32_bf16 v[30:33], v[130:133], v[220:223], v[30:33]
	v_mfma_f32_16x16x32_bf16 v[26:29], v[138:141], v[220:223], v[26:29]
	v_mfma_f32_16x16x32_bf16 v[14:17], v[130:133], v[228:231], v[14:17]
	v_mfma_f32_16x16x32_bf16 v[10:13], v[138:141], v[228:231], v[10:13]
	v_mfma_f32_16x16x32_bf16 v[62:65], v[134:137], v[190:193], v[62:65]
	v_mfma_f32_16x16x32_bf16 v[58:61], v[142:145], v[190:193], v[58:61]
	v_mfma_f32_16x16x32_bf16 v[46:49], v[134:137], v[216:219], v[46:49]
	v_mfma_f32_16x16x32_bf16 v[42:45], v[142:145], v[216:219], v[42:45]
	v_mfma_f32_16x16x32_bf16 v[30:33], v[134:137], v[224:227], v[30:33]
	v_mfma_f32_16x16x32_bf16 v[26:29], v[142:145], v[224:227], v[26:29]
	v_mfma_f32_16x16x32_bf16 v[14:17], v[134:137], v[232:235], v[14:17]
	v_mfma_f32_16x16x32_bf16 v[10:13], v[142:145], v[232:235], v[10:13]
	s_setprio 0
	s_setprio 1
	v_mfma_f32_16x16x32_bf16 v[54:57], v[146:149], v[186:189], v[54:57]
	v_mfma_f32_16x16x32_bf16 v[50:53], v[154:157], v[186:189], v[50:53]
	v_mfma_f32_16x16x32_bf16 v[38:41], v[146:149], v[194:197], v[38:41]
	v_mfma_f32_16x16x32_bf16 v[34:37], v[154:157], v[194:197], v[34:37]
	v_mfma_f32_16x16x32_bf16 v[22:25], v[146:149], v[220:223], v[22:25]
	v_mfma_f32_16x16x32_bf16 v[18:21], v[154:157], v[220:223], v[18:21]
	v_mfma_f32_16x16x32_bf16 v[6:9], v[146:149], v[228:231], v[6:9]
	v_mfma_f32_16x16x32_bf16 v[2:5], v[154:157], v[228:231], v[2:5]
	v_mfma_f32_16x16x32_bf16 v[54:57], v[150:153], v[190:193], v[54:57]
	v_mfma_f32_16x16x32_bf16 v[50:53], v[182:185], v[190:193], v[50:53]
	v_mfma_f32_16x16x32_bf16 v[38:41], v[150:153], v[216:219], v[38:41]
	v_mfma_f32_16x16x32_bf16 v[34:37], v[182:185], v[216:219], v[34:37]
	v_mfma_f32_16x16x32_bf16 v[22:25], v[150:153], v[224:227], v[22:25]
	v_mfma_f32_16x16x32_bf16 v[18:21], v[182:185], v[224:227], v[18:21]
	v_mfma_f32_16x16x32_bf16 v[6:9], v[150:153], v[232:235], v[6:9]
	v_mfma_f32_16x16x32_bf16 v[2:5], v[182:185], v[232:235], v[2:5]
	s_setprio 0
	s_barrier
	s_add_i32 s49, s49, 2
	s_add_u32 s47, s47, 0x100
	s_addc_u32 s48, s48, 0
	s_mov_b64 s[18:19], s[20:21]

; #define PG8_STAGE(bufoff, gbase, voff) do { _Pragma("unroll") for (int _i = 0; _i < 2; ++_i) \
;         __builtin_amdgcn_global_load_lds((const unsigned*)((const char*)(gbase) + (voff)[_i]), (PG8_LAS unsigned*)(lds + (bufoff) + ldsw + _i * 8192), 16, 0, 0); } while (0)
; #define PG8_LDA(dst, b, h) do { _Pragma("unroll") for (int m = 0; m < 4; ++m) _Pragma("unroll") for (int k = 0; k < 2; ++k) dst[m][k] = *(const PG8_LAS bf16x8*)(lds + PG8_SA(b, h) + aoff + m * 2048 + k * 1024); } while (0)
; #define PG8_LDB(dst, b, h) do { _Pragma("unroll") for (int n = 0; n < 2; ++n) _Pragma("unroll") for (int k = 0; k < 2; ++k) dst[n][k] = *(const PG8_LAS bf16x8*)(lds + PG8_SB(b, h) + boff + n * 2048 + k * 1024); } while (0)
; #define PG8_MMA(ai, bj, At, Bt) do { __builtin_amdgcn_s_setprio(1); _Pragma("unroll") for (int m = 0; m < 4; ++m) _Pragma("unroll") for (int n = 0; n < 2; ++n) _Pragma("unroll") for (int k = 0; k < 2; ++k) \
;         acc[ai][bj][m][n] = __builtin_amdgcn_mfma_f32_16x16x32_bf16(Bt[n][k], At[m][k], acc[ai][bj][m][n], 0, 0, 0); __builtin_amdgcn_s_setprio(0); } while (0)
; #define PG8_WAIT_V(n) asm volatile("s_waitcnt vmcnt(" #n ")" ::: "memory")
; #define PG8_WAIT_L(n) asm volatile("s_waitcnt lgkmcnt(" #n ")" ::: "memory")
; #define PG8_BAR __builtin_amdgcn_s_barrier()
; #define PG8_SCHED __builtin_amdgcn_sched_barrier(0)
; template <class Epi, class Sched, bool ALIGN_EPI = false, bool SP2 = false>
; __device__ __forceinline__ void gemm_phase(PG8_LAS unsigned char* lds, const Gemm g, const Sched& S, const Epi& E) {
;     ...
;     f32x4 acc[2][2][4][2];
; #pragma unroll
;     for (int a = 0; a < 2; ++a)
; #pragma unroll
;         for (int b = 0; b < 2; ++b)
; #pragma unroll
;             for (int m = 0; m < 4; ++m)
; #pragma unroll
;                 for (int n = 0; n < 2; ++n) acc[a][b][m][n] = (f32x4){0.f, 0.f, 0.f, 0.f};
;     ...
;             PG8_LDB(B0, 0, 0); PG8_LDB(B1, 0, 1); PG8_SCHED; PG8_LDA(At, 0, 0); PG8_STAGE(PG8_SA(1, 1), a1 + hstep, voffA);
;             PG8_WAIT_V(8); PG8_WAIT_L(0); PG8_BAR; PG8_MMA(0, 0, At, B0); PG8_MMA(0, 1, At, B1); PG8_BAR; PG8_SCHED;
;             PG8_LDA(At, 0, 1); PG8_STAGE(PG8_SB(0, 0), b2, voffB); PG8_STAGE(PG8_SB(0, 1), b2 + hstep, voffB); PG8_STAGE(PG8_SA(0, 0), a2, voffA);
;             PG8_WAIT_V(8); PG8_WAIT_L(0); PG8_BAR; PG8_MMA(1, 0, At, B0); PG8_MMA(1, 1, At, B1); PG8_BAR; PG8_SCHED;
.LBB0_492:
	s_ashr_i32 s17, s16, 31
	s_lshl_b64 s[18:19], s[16:17], 19
	s_add_u32 s18, s94, s18
	s_addc_u32 s19, s95, s19
	s_and_b64 s[20:21], s[4:5], exec
	s_cselect_b32 s17, s19, s23
	s_cselect_b32 s46, s18, s22
	s_ashr_i32 s15, s14, 31
	s_lshl_b64 s[20:21], s[14:15], 19
	s_add_u32 s20, s28, s20
	s_addc_u32 s21, s29, s21
	s_and_b64 s[26:27], s[4:5], exec
	s_cselect_b32 s15, s21, s25
	s_cselect_b32 s47, s20, s24
	s_add_u32 s22, s22, 0x40080
	s_addc_u32 s23, s23, 0
	s_add_u32 s48, s24, 0x100
	s_addc_u32 s49, s25, 0
	s_mov_b32 s50, -2
	s_add_u32 s24, s22, 0xfffc0080
	s_addc_u32 s25, s23, -1
	s_add_i32 s51, 0, 0x10000
	s_cmp_eq_u32 s50, 12
	s_cselect_b32 s27, s17, s25
	s_cselect_b32 s26, s46, s24
	v_add_u32_e32 v146, s51, v149
	s_cselect_b32 s25, s15, s49
	s_cselect_b32 s24, s47, s48
	s_add_i32 s54, 0, 0x14000
	ds_read_b128 v[142:145], v146
	ds_read_b128 v[152:155], v146 offset:1024
	ds_read_b128 v[172:175], v146 offset:2048
	ds_read_b128 v[176:179], v146 offset:3072
	v_add_u32_e32 v146, s54, v149
	ds_read_b128 v[180:183], v146
	ds_read_b128 v[184:187], v146 offset:1024
	ds_read_b128 v[188:191], v146 offset:2048
	ds_read_b128 v[192:195], v146 offset:3072
	s_add_i32 m0, s30, 0xc000
	ds_read_b128 v[196:199], v151
	ds_read_b128 v[214:217], v151 offset:1024
	ds_read_b128 v[218:221], v151 offset:2048
	ds_read_b128 v[222:225], v151 offset:3072
	ds_read_b128 v[226:229], v151 offset:4096
	ds_read_b128 v[230:233], v151 offset:5120
	ds_read_b128 v[234:237], v151 offset:6144
	ds_read_b128 v[238:241], v151 offset:7168
	global_load_lds_dwordx4 v138, s[22:23]
	s_add_i32 m0, s30, 0xe000
	s_nop 0
	global_load_lds_dwordx4 v140, s[22:23]
	s_waitcnt vmcnt(8)
	s_waitcnt lgkmcnt(0)
	s_barrier
	s_setprio 1
	s_waitcnt lgkmcnt(0)
	v_mfma_f32_16x16x32_bf16 v[126:129], v[142:145], v[196:199], 0
	v_mfma_f32_16x16x32_bf16 v[118:121], v[172:175], v[196:199], 0
	v_mfma_f32_16x16x32_bf16 v[110:113], v[142:145], v[218:221], 0
	v_mfma_f32_16x16x32_bf16 v[102:105], v[172:175], v[218:221], 0
	v_mfma_f32_16x16x32_bf16 v[94:97], v[142:145], v[226:229], 0
	v_mfma_f32_16x16x32_bf16 v[86:89], v[172:175], v[226:229], 0
	v_mfma_f32_16x16x32_bf16 v[78:81], v[142:145], v[234:237], 0
	v_mfma_f32_16x16x32_bf16 v[70:73], v[172:175], v[234:237], 0
	v_mfma_f32_16x16x32_bf16 v[126:129], v[152:155], v[214:217], v[126:129]
	v_mfma_f32_16x16x32_bf16 v[118:121], v[176:179], v[214:217], v[118:121]
	v_mfma_f32_16x16x32_bf16 v[110:113], v[152:155], v[222:225], v[110:113]
	v_mfma_f32_16x16x32_bf16 v[102:105], v[176:179], v[222:225], v[102:105]
	v_mfma_f32_16x16x32_bf16 v[94:97], v[152:155], v[230:233], v[94:97]
	v_mfma_f32_16x16x32_bf16 v[86:89], v[176:179], v[230:233], v[86:89]
	v_mfma_f32_16x16x32_bf16 v[78:81], v[152:155], v[238:241], v[78:81]
	v_mfma_f32_16x16x32_bf16 v[70:73], v[176:179], v[238:241], v[70:73]
	s_setprio 0
	s_setprio 1
	v_mfma_f32_16x16x32_bf16 v[122:125], v[180:183], v[196:199], 0
	v_mfma_f32_16x16x32_bf16 v[114:117], v[188:191], v[196:199], 0
	v_mfma_f32_16x16x32_bf16 v[106:109], v[180:183], v[218:221], 0
	v_mfma_f32_16x16x32_bf16 v[98:101], v[188:191], v[218:221], 0
	v_mfma_f32_16x16x32_bf16 v[90:93], v[180:183], v[226:229], 0
	v_mfma_f32_16x16x32_bf16 v[82:85], v[188:191], v[226:229], 0
	v_mfma_f32_16x16x32_bf16 v[74:77], v[180:183], v[234:237], 0
	v_mfma_f32_16x16x32_bf16 v[66:69], v[188:191], v[234:237], 0
	v_mfma_f32_16x16x32_bf16 v[122:125], v[184:187], v[214:217], v[122:125]
	v_mfma_f32_16x16x32_bf16 v[114:117], v[192:195], v[214:217], v[114:117]
	v_mfma_f32_16x16x32_bf16 v[106:109], v[184:187], v[222:225], v[106:109]
	v_mfma_f32_16x16x32_bf16 v[98:101], v[192:195], v[222:225], v[98:101]
	v_mfma_f32_16x16x32_bf16 v[90:93], v[184:187], v[230:233], v[90:93]
	v_mfma_f32_16x16x32_bf16 v[82:85], v[192:195], v[230:233], v[82:85]
	v_mfma_f32_16x16x32_bf16 v[74:77], v[184:187], v[238:241], v[74:77]
	v_mfma_f32_16x16x32_bf16 v[66:69], v[192:195], v[238:241], v[66:69]
	s_setprio 0
	s_barrier
	s_add_i32 s51, s51, s2
	s_mov_b32 m0, s51
	ds_read_b128 v[196:199], v151 offset:16384
	ds_read_b128 v[214:217], v151 offset:17408
	ds_read_b128 v[218:221], v151 offset:18432
	ds_read_b128 v[222:225], v151 offset:19456
	ds_read_b128 v[226:229], v151 offset:20480
	ds_read_b128 v[230:233], v151 offset:21504
	ds_read_b128 v[234:237], v151 offset:22528
	ds_read_b128 v[238:241], v151 offset:23552
	global_load_lds_dwordx4 v0, s[24:25]
	s_add_i32 m0, s51, 0x2000
	s_add_u32 s52, s24, 0x40000
	s_addc_u32 s53, s25, 0
	s_add_i32 s51, s54, s2
	global_load_lds_dwordx4 v130, s[24:25]
	s_mov_b32 m0, s51
	s_nop 0
	global_load_lds_dwordx4 v0, s[52:53]
	s_add_i32 m0, s51, 0x2000
	s_nop 0
	global_load_lds_dwordx4 v130, s[52:53]
	s_mov_b32 m0, s30
	s_nop 0
	global_load_lds_dwordx4 v134, s[26:27]
	s_mov_b32 m0, s31
	s_nop 0
	global_load_lds_dwordx4 v132, s[26:27]
	s_waitcnt vmcnt(8)
	s_waitcnt lgkmcnt(0)
	s_barrier
; #define PG8_STAGE(bufoff, gbase, voff) do { _Pragma("unroll") for (int _i = 0; _i < 2; ++_i) \
;         __builtin_amdgcn_global_load_lds((const unsigned*)((const char*)(gbase) + (voff)[_i]), (PG8_LAS unsigned*)(lds + (bufoff) + ldsw + _i * 8192), 16, 0, 0); } while (0)
; #define PG8_LDA(dst, b, h) do { _Pragma("unroll") for (int m = 0; m < 4; ++m) _Pragma("unroll") for (int k = 0; k < 2; ++k) dst[m][k] = *(const PG8_LAS bf16x8*)(lds + PG8_SA(b, h) + aoff + m * 2048 + k * 1024); } while (0)
; #define PG8_LDB(dst, b, h) do { _Pragma("unroll") for (int n = 0; n < 2; ++n) _Pragma("unroll") for (int k = 0; k < 2; ++k) dst[n][k] = *(const PG8_LAS bf16x8*)(lds + PG8_SB(b, h) + boff + n * 2048 + k * 1024); } while (0)
; #define PG8_MMA(ai, bj, At, Bt) do { __builtin_amdgcn_s_setprio(1); _Pragma("unroll") for (int m = 0; m < 4; ++m) _Pragma("unroll") for (int n = 0; n < 2; ++n) _Pragma("unroll") for (int k = 0; k < 2; ++k) \
;         acc[ai][bj][m][n] = __builtin_amdgcn_mfma_f32_16x16x32_bf16(Bt[n][k], At[m][k], acc[ai][bj][m][n], 0, 0, 0); __builtin_amdgcn_s_setprio(0); } while (0)
; #define PG8_WAIT_V(n) asm volatile("s_waitcnt vmcnt(" #n ")" ::: "memory")
; #define PG8_WAIT_L(n) asm volatile("s_waitcnt lgkmcnt(" #n ")" ::: "memory")
; #define PG8_BAR __builtin_amdgcn_s_barrier()
; #define PG8_SCHED __builtin_amdgcn_sched_barrier(0)
; template <class Epi, class Sched, bool ALIGN_EPI = false, bool SP2 = false>
; __device__ __forceinline__ void gemm_phase(PG8_LAS unsigned char* lds, const Gemm g, const Sched& S, const Epi& E) {
;     ...
;             PG8_WAIT_V(8); PG8_WAIT_L(0); PG8_BAR; PG8_MMA(1, 0, At, B0); PG8_MMA(1, 1, At, B1); PG8_BAR; PG8_SCHED;
;             PG8_LDB(B0, 1, 0); PG8_LDB(B1, 1, 1); PG8_SCHED; PG8_LDA(At, 1, 0); PG8_STAGE(PG8_SA(0, 1), a2 + hstep, voffA);
;             PG8_WAIT_V(8); PG8_WAIT_L(0); PG8_BAR; PG8_MMA(0, 0, At, B0); PG8_MMA(0, 1, At, B1); PG8_BAR; PG8_SCHED;
	s_setprio 1
	s_waitcnt lgkmcnt(0)
	v_mfma_f32_16x16x32_bf16 v[62:65], v[142:145], v[196:199], 0
	v_mfma_f32_16x16x32_bf16 v[54:57], v[172:175], v[196:199], 0
	v_mfma_f32_16x16x32_bf16 v[46:49], v[142:145], v[218:221], 0
	v_mfma_f32_16x16x32_bf16 v[38:41], v[172:175], v[218:221], 0
	v_mfma_f32_16x16x32_bf16 v[30:33], v[142:145], v[226:229], 0
	v_mfma_f32_16x16x32_bf16 v[22:25], v[172:175], v[226:229], 0
	v_mfma_f32_16x16x32_bf16 v[14:17], v[142:145], v[234:237], 0
	v_mfma_f32_16x16x32_bf16 v[6:9], v[172:175], v[234:237], 0
	v_mfma_f32_16x16x32_bf16 v[62:65], v[152:155], v[214:217], v[62:65]
	v_mfma_f32_16x16x32_bf16 v[54:57], v[176:179], v[214:217], v[54:57]
	v_mfma_f32_16x16x32_bf16 v[46:49], v[152:155], v[222:225], v[46:49]
	v_mfma_f32_16x16x32_bf16 v[38:41], v[176:179], v[222:225], v[38:41]
	v_mfma_f32_16x16x32_bf16 v[30:33], v[152:155], v[230:233], v[30:33]
	v_mfma_f32_16x16x32_bf16 v[22:25], v[176:179], v[230:233], v[22:25]
	v_mfma_f32_16x16x32_bf16 v[14:17], v[152:155], v[238:241], v[14:17]
	v_mfma_f32_16x16x32_bf16 v[6:9], v[176:179], v[238:241], v[6:9]
	s_setprio 0
	s_setprio 1
	v_mfma_f32_16x16x32_bf16 v[58:61], v[180:183], v[196:199], 0
	v_mfma_f32_16x16x32_bf16 v[50:53], v[188:191], v[196:199], 0
	v_mfma_f32_16x16x32_bf16 v[42:45], v[180:183], v[218:221], 0
	v_mfma_f32_16x16x32_bf16 v[34:37], v[188:191], v[218:221], 0
	v_mfma_f32_16x16x32_bf16 v[26:29], v[180:183], v[226:229], 0
	v_mfma_f32_16x16x32_bf16 v[18:21], v[188:191], v[226:229], 0
	v_mfma_f32_16x16x32_bf16 v[10:13], v[180:183], v[234:237], 0
	v_mfma_f32_16x16x32_bf16 v[2:5], v[188:191], v[234:237], 0
	v_mfma_f32_16x16x32_bf16 v[58:61], v[184:187], v[214:217], v[58:61]
	v_mfma_f32_16x16x32_bf16 v[50:53], v[192:195], v[214:217], v[50:53]
	v_mfma_f32_16x16x32_bf16 v[42:45], v[184:187], v[222:225], v[42:45]
	v_mfma_f32_16x16x32_bf16 v[34:37], v[192:195], v[222:225], v[34:37]
	v_mfma_f32_16x16x32_bf16 v[26:29], v[184:187], v[230:233], v[26:29]
	v_mfma_f32_16x16x32_bf16 v[18:21], v[192:195], v[230:233], v[18:21]
	v_mfma_f32_16x16x32_bf16 v[10:13], v[184:187], v[238:241], v[10:13]
	v_mfma_f32_16x16x32_bf16 v[2:5], v[192:195], v[238:241], v[2:5]
	s_setprio 0
	s_barrier
	s_add_i32 s51, 0, 0x18000
	v_add_u32_e32 v158, s51, v149
	s_add_i32 s52, 0, 0x1c000
	ds_read_b128 v[142:145], v158
	ds_read_b128 v[152:155], v158 offset:1024
	ds_read_b128 v[172:175], v158 offset:2048
	ds_read_b128 v[176:179], v158 offset:3072
	v_add_u32_e32 v158, s52, v149
	ds_read_b128 v[180:183], v158
	ds_read_b128 v[184:187], v158 offset:1024
	ds_read_b128 v[188:191], v158 offset:2048
	ds_read_b128 v[192:195], v158 offset:3072
	s_add_u32 s26, s26, 0x40000
	s_addc_u32 s27, s27, 0
	s_mov_b32 m0, s34
	ds_read_b128 v[196:199], v151 offset:32768
	ds_read_b128 v[214:217], v151 offset:33792
	ds_read_b128 v[218:221], v151 offset:34816
	ds_read_b128 v[222:225], v151 offset:35840
	ds_read_b128 v[226:229], v151 offset:36864
	ds_read_b128 v[230:233], v151 offset:37888
	ds_read_b128 v[234:237], v151 offset:38912
	ds_read_b128 v[238:241], v151 offset:39936
	global_load_lds_dwordx4 v134, s[26:27]
	s_mov_b32 m0, s35
	s_nop 0
	global_load_lds_dwordx4 v132, s[26:27]
	s_waitcnt vmcnt(8)
	s_waitcnt lgkmcnt(0)
	s_barrier
	s_setprio 1
	s_waitcnt lgkmcnt(0)
	v_mfma_f32_16x16x32_bf16 v[126:129], v[142:145], v[196:199], v[126:129]
	v_mfma_f32_16x16x32_bf16 v[118:121], v[172:175], v[196:199], v[118:121]
	v_mfma_f32_16x16x32_bf16 v[110:113], v[142:145], v[218:221], v[110:113]
	v_mfma_f32_16x16x32_bf16 v[102:105], v[172:175], v[218:221], v[102:105]
	v_mfma_f32_16x16x32_bf16 v[94:97], v[142:145], v[226:229], v[94:97]
	v_mfma_f32_16x16x32_bf16 v[86:89], v[172:175], v[226:229], v[86:89]
	v_mfma_f32_16x16x32_bf16 v[78:81], v[142:145], v[234:237], v[78:81]
	v_mfma_f32_16x16x32_bf16 v[70:73], v[172:175], v[234:237], v[70:73]
	v_mfma_f32_16x16x32_bf16 v[126:129], v[152:155], v[214:217], v[126:129]
	v_mfma_f32_16x16x32_bf16 v[118:121], v[176:179], v[214:217], v[118:121]
	v_mfma_f32_16x16x32_bf16 v[110:113], v[152:155], v[222:225], v[110:113]
	v_mfma_f32_16x16x32_bf16 v[102:105], v[176:179], v[222:225], v[102:105]
	v_mfma_f32_16x16x32_bf16 v[94:97], v[152:155], v[230:233], v[94:97]
	v_mfma_f32_16x16x32_bf16 v[86:89], v[176:179], v[230:233], v[86:89]
	v_mfma_f32_16x16x32_bf16 v[78:81], v[152:155], v[238:241], v[78:81]
	v_mfma_f32_16x16x32_bf16 v[70:73], v[176:179], v[238:241], v[70:73]
	s_setprio 0
	s_setprio 1
	v_mfma_f32_16x16x32_bf16 v[122:125], v[180:183], v[196:199], v[122:125]
	v_mfma_f32_16x16x32_bf16 v[114:117], v[188:191], v[196:199], v[114:117]
	v_mfma_f32_16x16x32_bf16 v[106:109], v[180:183], v[218:221], v[106:109]
	v_mfma_f32_16x16x32_bf16 v[98:101], v[188:191], v[218:221], v[98:101]
	v_mfma_f32_16x16x32_bf16 v[90:93], v[180:183], v[226:229], v[90:93]
	v_mfma_f32_16x16x32_bf16 v[82:85], v[188:191], v[226:229], v[82:85]
	v_mfma_f32_16x16x32_bf16 v[74:77], v[180:183], v[234:237], v[74:77]
	v_mfma_f32_16x16x32_bf16 v[66:69], v[188:191], v[234:237], v[66:69]
	v_mfma_f32_16x16x32_bf16 v[122:125], v[184:187], v[214:217], v[122:125]
	v_mfma_f32_16x16x32_bf16 v[114:117], v[192:195], v[214:217], v[114:117]
	v_mfma_f32_16x16x32_bf16 v[106:109], v[184:187], v[222:225], v[106:109]
	v_mfma_f32_16x16x32_bf16 v[98:101], v[192:195], v[222:225], v[98:101]
	v_mfma_f32_16x16x32_bf16 v[90:93], v[184:187], v[230:233], v[90:93]
	v_mfma_f32_16x16x32_bf16 v[82:85], v[192:195], v[230:233], v[82:85]
	v_mfma_f32_16x16x32_bf16 v[74:77], v[184:187], v[238:241], v[74:77]
	v_mfma_f32_16x16x32_bf16 v[66:69], v[192:195], v[238:241], v[66:69]
	s_setprio 0
	s_barrier
; #define PG8_STAGE(bufoff, gbase, voff) do { _Pragma("unroll") for (int _i = 0; _i < 2; ++_i) \
;         __builtin_amdgcn_global_load_lds((const unsigned*)((const char*)(gbase) + (voff)[_i]), (PG8_LAS unsigned*)(lds + (bufoff) + ldsw + _i * 8192), 16, 0, 0); } while (0)
; #define PG8_LDA(dst, b, h) do { _Pragma("unroll") for (int m = 0; m < 4; ++m) _Pragma("unroll") for (int k = 0; k < 2; ++k) dst[m][k] = *(const PG8_LAS bf16x8*)(lds + PG8_SA(b, h) + aoff + m * 2048 + k * 1024); } while (0)
; #define PG8_MMA(ai, bj, At, Bt) do { __builtin_amdgcn_s_setprio(1); _Pragma("unroll") for (int m = 0; m < 4; ++m) _Pragma("unroll") for (int n = 0; n < 2; ++n) _Pragma("unroll") for (int k = 0; k < 2; ++k) \
;         acc[ai][bj][m][n] = __builtin_amdgcn_mfma_f32_16x16x32_bf16(Bt[n][k], At[m][k], acc[ai][bj][m][n], 0, 0, 0); __builtin_amdgcn_s_setprio(0); } while (0)
; #define PG8_WAIT_V(n) asm volatile("s_waitcnt vmcnt(" #n ")" ::: "memory")
; #define PG8_WAIT_L(n) asm volatile("s_waitcnt lgkmcnt(" #n ")" ::: "memory")
; #define PG8_BAR __builtin_amdgcn_s_barrier()
; #define PG8_SCHED __builtin_amdgcn_sched_barrier(0)
; template <class Epi, class Sched, bool ALIGN_EPI = false, bool SP2 = false>
; __device__ __forceinline__ void gemm_phase(PG8_LAS unsigned char* lds, const Gemm g, const Sched& S, const Epi& E) {
;     ...
;         for (int t = 0; t < nt; t += 2) {
;             const bool last = (t == nt - 2);
;             const char* a1 = cA + (size_t)(t + 1) * kstep;
;             const char* a2 = last ? nA : cA + (size_t)(t + 2) * kstep; const char* b2 = last ? nB : cB + (size_t)(t + 2) * kstep;
;             const char* a3 = a2 + kstep; const char* b3 = b2 + kstep;
;     ...
;             PG8_LDA(At, 1, 1); PG8_STAGE(PG8_SB(1, 0), b3, voffB); PG8_STAGE(PG8_SB(1, 1), b3 + hstep, voffB); PG8_STAGE(PG8_SA(1, 0), a3, voffA);
;             PG8_WAIT_V(8); PG8_WAIT_L(0); PG8_BAR; PG8_MMA(1, 0, At, B0); PG8_MMA(1, 1, At, B1); PG8_BAR; PG8_SCHED;
	s_add_u32 s98, s26, 0xfffc0080
	s_addc_u32 s99, s27, -1
	s_add_i32 s26, s51, s2
	s_add_u32 s100, s24, 0x80
	s_addc_u32 s101, s25, 0
	s_mov_b32 m0, s26
	ds_read_b128 v[196:199], v151 offset:49152
	ds_read_b128 v[214:217], v151 offset:50176
	ds_read_b128 v[218:221], v151 offset:51200
	ds_read_b128 v[222:225], v151 offset:52224
	ds_read_b128 v[226:229], v151 offset:53248
	ds_read_b128 v[230:233], v151 offset:54272
	ds_read_b128 v[234:237], v151 offset:55296
	ds_read_b128 v[238:241], v151 offset:56320
	global_load_lds_dwordx4 v0, s[100:101]
	s_add_i32 m0, s26, 0x2000
	s_add_u32 s24, s24, 0x40080
	s_addc_u32 s25, s25, 0
	s_add_i32 s26, s52, s2
	global_load_lds_dwordx4 v130, s[100:101]
	s_mov_b32 m0, s26
	s_nop 0
	global_load_lds_dwordx4 v0, s[24:25]
	s_add_i32 m0, s26, 0x2000
	s_nop 0
	global_load_lds_dwordx4 v130, s[24:25]
	s_mov_b32 m0, s37
	s_nop 0
	global_load_lds_dwordx4 v134, s[98:99]
	s_mov_b32 m0, s38
	s_nop 0
	global_load_lds_dwordx4 v132, s[98:99]
	s_waitcnt vmcnt(8)
	s_waitcnt lgkmcnt(0)
	s_barrier
	s_setprio 1
	s_waitcnt lgkmcnt(0)
	v_mfma_f32_16x16x32_bf16 v[62:65], v[142:145], v[196:199], v[62:65]
	v_mfma_f32_16x16x32_bf16 v[54:57], v[172:175], v[196:199], v[54:57]
	v_mfma_f32_16x16x32_bf16 v[46:49], v[142:145], v[218:221], v[46:49]
	v_mfma_f32_16x16x32_bf16 v[38:41], v[172:175], v[218:221], v[38:41]
	v_mfma_f32_16x16x32_bf16 v[30:33], v[142:145], v[226:229], v[30:33]
	v_mfma_f32_16x16x32_bf16 v[22:25], v[172:175], v[226:229], v[22:25]
	v_mfma_f32_16x16x32_bf16 v[14:17], v[142:145], v[234:237], v[14:17]
	v_mfma_f32_16x16x32_bf16 v[6:9], v[172:175], v[234:237], v[6:9]
	v_mfma_f32_16x16x32_bf16 v[62:65], v[152:155], v[214:217], v[62:65]
	v_mfma_f32_16x16x32_bf16 v[54:57], v[176:179], v[214:217], v[54:57]
	v_mfma_f32_16x16x32_bf16 v[46:49], v[152:155], v[222:225], v[46:49]
	v_mfma_f32_16x16x32_bf16 v[38:41], v[176:179], v[222:225], v[38:41]
	v_mfma_f32_16x16x32_bf16 v[30:33], v[152:155], v[230:233], v[30:33]
	v_mfma_f32_16x16x32_bf16 v[22:25], v[176:179], v[230:233], v[22:25]
	v_mfma_f32_16x16x32_bf16 v[14:17], v[152:155], v[238:241], v[14:17]
	v_mfma_f32_16x16x32_bf16 v[6:9], v[176:179], v[238:241], v[6:9]
	s_setprio 0
	s_setprio 1
	v_mfma_f32_16x16x32_bf16 v[58:61], v[180:183], v[196:199], v[58:61]
	v_mfma_f32_16x16x32_bf16 v[50:53], v[188:191], v[196:199], v[50:53]
	v_mfma_f32_16x16x32_bf16 v[42:45], v[180:183], v[218:221], v[42:45]
	v_mfma_f32_16x16x32_bf16 v[34:37], v[188:191], v[218:221], v[34:37]
	v_mfma_f32_16x16x32_bf16 v[26:29], v[180:183], v[226:229], v[26:29]
	v_mfma_f32_16x16x32_bf16 v[18:21], v[188:191], v[226:229], v[18:21]
	v_mfma_f32_16x16x32_bf16 v[10:13], v[180:183], v[234:237], v[10:13]
	v_mfma_f32_16x16x32_bf16 v[2:5], v[188:191], v[234:237], v[2:5]
	v_mfma_f32_16x16x32_bf16 v[58:61], v[184:187], v[214:217], v[58:61]
	v_mfma_f32_16x16x32_bf16 v[50:53], v[192:195], v[214:217], v[50:53]
	v_mfma_f32_16x16x32_bf16 v[42:45], v[184:187], v[222:225], v[42:45]
	v_mfma_f32_16x16x32_bf16 v[34:37], v[192:195], v[222:225], v[34:37]
	v_mfma_f32_16x16x32_bf16 v[26:29], v[184:187], v[230:233], v[26:29]
	v_mfma_f32_16x16x32_bf16 v[18:21], v[192:195], v[230:233], v[18:21]
	v_mfma_f32_16x16x32_bf16 v[10:13], v[184:187], v[238:241], v[10:13]
	v_mfma_f32_16x16x32_bf16 v[2:5], v[192:195], v[238:241], v[2:5]
	s_setprio 0
	s_barrier
	s_add_i32 s50, s50, 2
	s_add_u32 s22, s22, 0x100
	s_addc_u32 s23, s23, 0
	s_add_u32 s48, s48, 0x100
	s_addc_u32 s49, s49, 0
